# nontemporal hint on the FFN-up activation stores (streaming 369 MB, keeps weights and xb in L2)
# speedup vs baseline: 1.0337x; 1.0032x over previous
.Lst_out_s3:
	s_lshl_b32 s8, s0, 8
	s_add_i32 s8, s8, s56
	s_lshl_b32 s9, s1, 7
	s_add_i32 s9, s9, s49
	s_lshl_b32 s10, s0, 3
	s_lshr_b32 s11, s56, 5
	s_add_i32 s10, s10, s11
	v_add_u32_e32 v200, s8, v163
	v_lshlrev_b32_e32 v213, 2, v200
	global_load_dword v188, v213, s[12:13]
	global_load_dword v189, v213, s[12:13] offset:64
	global_load_dword v190, v213, s[12:13] offset:128
	global_load_dword v191, v213, s[12:13] offset:192
	global_load_dword v192, v213, s[12:13] offset:256
	global_load_dword v193, v213, s[12:13] offset:320
	global_load_dword v194, v213, s[12:13] offset:384
	global_load_dword v195, v213, s[12:13] offset:448
	v_lshl_add_u32 v201, v225, 3, s9
	v_lshlrev_b32_e32 v212, 2, v201
	global_load_dwordx4 v[76:79], v212, s[82:83]
	v_add_u32_e32 v213, 0xb000, v212
	global_load_dwordx4 v[80:83], v213, s[82:83]
	v_add_u32_e32 v213, 0x16000, v212
	global_load_dwordx4 v[84:87], v213, s[82:83]
	global_load_dwordx4 v[88:91], v212, s[84:85]
	v_add_u32_e32 v213, 0x5800, v212
	global_load_dwordx4 v[92:95], v213, s[82:83]
	v_add_u32_e32 v213, 0x10800, v212
	global_load_dwordx4 v[96:99], v213, s[82:83]
	v_add_u32_e32 v213, 0x1b800, v212
	global_load_dwordx4 v[100:103], v213, s[82:83]
	v_add_u32_e32 v213, 0x5800, v212
	global_load_dwordx4 v[104:107], v213, s[84:85]
	v_mul_u32_u24_e32 v215, 0x2c00, v200
	v_lshl_add_u32 v215, v201, 1, v215
	v_add_u32_e32 v213, s10, v163
	v_mul_u32_u24_e32 v217, 0xb000, v213
	v_add_u32_e32 v217, v217, v212
	v_cmp_gt_u32_e64 s[8:9], 2, v163
	v_cmp_lt_u32_e64 s[10:11], 13, v163
	v_cmp_lt_u32_e32 vcc, 1, v163
	v_mov_b32_e32 v214, 1.0
	v_mov_b32_e32 v216, 0xbfb8aa3b
	v_mov_b32_e32 v108, 0x3727c5ac
	s_waitcnt vmcnt(8)
	v_fmamk_f32 v188, v188, 0x3a000000, v108
	v_fmamk_f32 v189, v189, 0x3a000000, v108
	v_fmamk_f32 v190, v190, 0x3a000000, v108
	v_fmamk_f32 v191, v191, 0x3a000000, v108
	v_fmamk_f32 v192, v192, 0x3a000000, v108
	v_fmamk_f32 v193, v193, 0x3a000000, v108
	v_fmamk_f32 v194, v194, 0x3a000000, v108
	v_fmamk_f32 v195, v195, 0x3a000000, v108
	v_rsq_f32_e32 v188, v188
	v_rsq_f32_e32 v189, v189
	v_rsq_f32_e32 v190, v190
	v_rsq_f32_e32 v191, v191
	v_rsq_f32_e32 v192, v192
	v_rsq_f32_e32 v193, v193
	v_rsq_f32_e32 v194, v194
	v_rsq_f32_e32 v195, v195
	v_pk_mul_f32 v[158:159], v[158:159], v[188:189] op_sel_hi:[1,0]
	v_pk_mul_f32 v[160:161], v[160:161], v[188:189] op_sel_hi:[1,0]
	v_pk_mul_f32 v[60:61], v[60:61], v[188:189] op_sel_hi:[1,0]
	v_pk_mul_f32 v[62:63], v[62:63], v[188:189] op_sel_hi:[1,0]
	v_pk_mul_f32 v[154:155], v[154:155], v[188:189] op_sel_hi:[1,0]
	v_pk_mul_f32 v[156:157], v[156:157], v[188:189] op_sel_hi:[1,0]
	v_pk_mul_f32 v[56:57], v[56:57], v[188:189] op_sel_hi:[1,0]
	v_pk_mul_f32 v[58:59], v[58:59], v[188:189] op_sel_hi:[1,0]
	v_pk_mul_f32 v[150:151], v[150:151], v[188:189] op_sel:[0,1] op_sel_hi:[1,1]
	v_pk_mul_f32 v[152:153], v[152:153], v[188:189] op_sel:[0,1] op_sel_hi:[1,1]
	v_pk_mul_f32 v[52:53], v[52:53], v[188:189] op_sel:[0,1] op_sel_hi:[1,1]
	v_pk_mul_f32 v[54:55], v[54:55], v[188:189] op_sel:[0,1] op_sel_hi:[1,1]
	v_pk_mul_f32 v[142:143], v[142:143], v[188:189] op_sel:[0,1] op_sel_hi:[1,1]
	v_pk_mul_f32 v[144:145], v[144:145], v[188:189] op_sel:[0,1] op_sel_hi:[1,1]
	v_pk_mul_f32 v[44:45], v[44:45], v[188:189] op_sel:[0,1] op_sel_hi:[1,1]
	v_pk_mul_f32 v[46:47], v[46:47], v[188:189] op_sel:[0,1] op_sel_hi:[1,1]
	v_pk_mul_f32 v[146:147], v[146:147], v[190:191] op_sel_hi:[1,0]
	v_pk_mul_f32 v[148:149], v[148:149], v[190:191] op_sel_hi:[1,0]
	v_pk_mul_f32 v[48:49], v[48:49], v[190:191] op_sel_hi:[1,0]
	v_pk_mul_f32 v[50:51], v[50:51], v[190:191] op_sel_hi:[1,0]
	v_pk_mul_f32 v[134:135], v[134:135], v[190:191] op_sel_hi:[1,0]
	v_pk_mul_f32 v[136:137], v[136:137], v[190:191] op_sel_hi:[1,0]
	v_pk_mul_f32 v[36:37], v[36:37], v[190:191] op_sel_hi:[1,0]
	v_pk_mul_f32 v[38:39], v[38:39], v[190:191] op_sel_hi:[1,0]
	v_pk_mul_f32 v[138:139], v[138:139], v[190:191] op_sel:[0,1] op_sel_hi:[1,1]
	v_pk_mul_f32 v[140:141], v[140:141], v[190:191] op_sel:[0,1] op_sel_hi:[1,1]
	v_pk_mul_f32 v[40:41], v[40:41], v[190:191] op_sel:[0,1] op_sel_hi:[1,1]
	v_pk_mul_f32 v[42:43], v[42:43], v[190:191] op_sel:[0,1] op_sel_hi:[1,1]
	v_pk_mul_f32 v[130:131], v[130:131], v[190:191] op_sel:[0,1] op_sel_hi:[1,1]
	v_pk_mul_f32 v[132:133], v[132:133], v[190:191] op_sel:[0,1] op_sel_hi:[1,1]
	v_pk_mul_f32 v[32:33], v[32:33], v[190:191] op_sel:[0,1] op_sel_hi:[1,1]
	v_pk_mul_f32 v[34:35], v[34:35], v[190:191] op_sel:[0,1] op_sel_hi:[1,1]
	v_pk_mul_f32 v[126:127], v[126:127], v[192:193] op_sel_hi:[1,0]
	v_pk_mul_f32 v[128:129], v[128:129], v[192:193] op_sel_hi:[1,0]
	v_pk_mul_f32 v[28:29], v[28:29], v[192:193] op_sel_hi:[1,0]
	v_pk_mul_f32 v[30:31], v[30:31], v[192:193] op_sel_hi:[1,0]
	v_pk_mul_f32 v[118:119], v[118:119], v[192:193] op_sel_hi:[1,0]
	v_pk_mul_f32 v[120:121], v[120:121], v[192:193] op_sel_hi:[1,0]
	v_pk_mul_f32 v[16:17], v[16:17], v[192:193] op_sel_hi:[1,0]
	v_pk_mul_f32 v[18:19], v[18:19], v[192:193] op_sel_hi:[1,0]
	v_pk_mul_f32 v[122:123], v[122:123], v[192:193] op_sel:[0,1] op_sel_hi:[1,1]
	v_pk_mul_f32 v[124:125], v[124:125], v[192:193] op_sel:[0,1] op_sel_hi:[1,1]
	v_pk_mul_f32 v[24:25], v[24:25], v[192:193] op_sel:[0,1] op_sel_hi:[1,1]
	v_pk_mul_f32 v[26:27], v[26:27], v[192:193] op_sel:[0,1] op_sel_hi:[1,1]
	v_pk_mul_f32 v[110:111], v[110:111], v[192:193] op_sel:[0,1] op_sel_hi:[1,1]
	v_pk_mul_f32 v[112:113], v[112:113], v[192:193] op_sel:[0,1] op_sel_hi:[1,1]
	v_pk_mul_f32 v[12:13], v[12:13], v[192:193] op_sel:[0,1] op_sel_hi:[1,1]
	v_pk_mul_f32 v[14:15], v[14:15], v[192:193] op_sel:[0,1] op_sel_hi:[1,1]
	v_pk_mul_f32 v[114:115], v[114:115], v[194:195] op_sel_hi:[1,0]
	v_pk_mul_f32 v[116:117], v[116:117], v[194:195] op_sel_hi:[1,0]
	v_pk_mul_f32 v[20:21], v[20:21], v[194:195] op_sel_hi:[1,0]
	v_pk_mul_f32 v[22:23], v[22:23], v[194:195] op_sel_hi:[1,0]
	v_pk_mul_f32 v[68:69], v[68:69], v[194:195] op_sel_hi:[1,0]
	v_pk_mul_f32 v[70:71], v[70:71], v[194:195] op_sel_hi:[1,0]
	v_pk_mul_f32 v[8:9], v[8:9], v[194:195] op_sel_hi:[1,0]
	v_pk_mul_f32 v[10:11], v[10:11], v[194:195] op_sel_hi:[1,0]
	v_pk_mul_f32 v[72:73], v[72:73], v[194:195] op_sel:[0,1] op_sel_hi:[1,1]
	v_pk_mul_f32 v[74:75], v[74:75], v[194:195] op_sel:[0,1] op_sel_hi:[1,1]
	v_pk_mul_f32 v[4:5], v[4:5], v[194:195] op_sel:[0,1] op_sel_hi:[1,1]
	v_pk_mul_f32 v[6:7], v[6:7], v[194:195] op_sel:[0,1] op_sel_hi:[1,1]
	v_pk_mul_f32 v[64:65], v[64:65], v[194:195] op_sel:[0,1] op_sel_hi:[1,1]
	v_pk_mul_f32 v[66:67], v[66:67], v[194:195] op_sel:[0,1] op_sel_hi:[1,1]
	v_pk_mul_f32 v[0:1], v[0:1], v[194:195] op_sel:[0,1] op_sel_hi:[1,1]
	v_pk_mul_f32 v[2:3], v[2:3], v[194:195] op_sel:[0,1] op_sel_hi:[1,1]
	s_nop 1
	s_mov_b64 exec, s[8:9]
	v_add_u32_e32 v213, 0x5800, v217
	global_store_dwordx4 v217, v[158:161], s[70:71]
	global_store_dwordx4 v213, v[154:157], s[70:71]
	global_store_dwordx4 v217, v[60:63], s[70:71] offset:16
	global_store_dwordx4 v213, v[56:59], s[70:71] offset:16
	s_mov_b64 exec, s[10:11]
	v_add_u32_e32 v213, 0xfff7c000, v217
	global_store_dwordx4 v213, v[72:75], s[70:71]
	global_store_dwordx4 v213, v[4:7], s[70:71] offset:16
	v_add_u32_e32 v213, 0xfff81800, v217
	global_store_dwordx4 v213, v[64:67], s[70:71]
	global_store_dwordx4 v213, v[0:3], s[70:71] offset:16
	s_mov_b64 exec, -1
	v_add_u32_e32 v213, 0x1b800, v212
	global_load_dwordx4 v[204:207], v213, s[82:83] offset:16
	v_add_u32_e32 v213, 0x5800, v212
	global_load_dwordx4 v[208:211], v213, s[84:85] offset:16
	s_waitcnt vmcnt(10)
	v_pk_fma_f32 v[188:189], v[158:159], v[84:85], v[88:89]
	v_pk_fma_f32 v[190:191], v[160:161], v[86:87], v[90:91]
	v_pk_fma_f32 v[192:193], v[154:155], v[100:101], v[104:105]
	v_pk_fma_f32 v[194:195], v[156:157], v[102:103], v[106:107]
	v_fmac_f32_dpp v188, v158, v80 row_shr:1 row_mask:0xf bank_mask:0xf
	v_fmac_f32_dpp v189, v159, v81 row_shr:1 row_mask:0xf bank_mask:0xf
	v_fmac_f32_dpp v190, v160, v82 row_shr:1 row_mask:0xf bank_mask:0xf
	v_fmac_f32_dpp v191, v161, v83 row_shr:1 row_mask:0xf bank_mask:0xf
	v_fmac_f32_dpp v192, v154, v96 row_shr:1 row_mask:0xf bank_mask:0xf
	v_fmac_f32_dpp v193, v155, v97 row_shr:1 row_mask:0xf bank_mask:0xf
	v_fmac_f32_dpp v194, v156, v98 row_shr:1 row_mask:0xf bank_mask:0xf
	v_fmac_f32_dpp v195, v157, v99 row_shr:1 row_mask:0xf bank_mask:0xf
	v_fmac_f32_dpp v188, v158, v76 row_shr:2 row_mask:0xf bank_mask:0xf
	v_fmac_f32_dpp v189, v159, v77 row_shr:2 row_mask:0xf bank_mask:0xf
	v_fmac_f32_dpp v190, v160, v78 row_shr:2 row_mask:0xf bank_mask:0xf
	v_fmac_f32_dpp v191, v161, v79 row_shr:2 row_mask:0xf bank_mask:0xf
	v_fmac_f32_dpp v192, v154, v92 row_shr:2 row_mask:0xf bank_mask:0xf
	v_fmac_f32_dpp v193, v155, v93 row_shr:2 row_mask:0xf bank_mask:0xf
	v_fmac_f32_dpp v194, v156, v94 row_shr:2 row_mask:0xf bank_mask:0xf
	v_fmac_f32_dpp v195, v157, v95 row_shr:2 row_mask:0xf bank_mask:0xf
	v_pk_mul_f32 v[196:197], v[188:189], v[216:217] op_sel_hi:[1,0]
	v_pk_mul_f32 v[198:199], v[190:191], v[216:217] op_sel_hi:[1,0]
	v_exp_f32_e32 v196, v196
	v_exp_f32_e32 v197, v197
	v_exp_f32_e32 v198, v198
	v_exp_f32_e32 v199, v199
	v_pk_add_f32 v[196:197], v[196:197], v[214:215] op_sel_hi:[1,0]
	v_pk_add_f32 v[198:199], v[198:199], v[214:215] op_sel_hi:[1,0]
	v_rcp_f32_e32 v196, v196
	v_rcp_f32_e32 v197, v197
	v_rcp_f32_e32 v198, v198
	v_rcp_f32_e32 v199, v199
	v_pk_mul_f32 v[188:189], v[188:189], v[196:197]
	v_pk_mul_f32 v[190:191], v[190:191], v[198:199]
	v_pk_mul_f32 v[188:189], v[188:189], v[192:193]
	v_pk_mul_f32 v[190:191], v[190:191], v[194:195]
	v_cvt_pk_bf16_f32 v200, v188, v189
	v_cvt_pk_bf16_f32 v201, v190, v191
	v_pk_fma_f32 v[188:189], v[150:151], v[84:85], v[88:89]
	v_pk_fma_f32 v[190:191], v[152:153], v[86:87], v[90:91]
	v_pk_fma_f32 v[192:193], v[142:143], v[100:101], v[104:105]
	v_pk_fma_f32 v[194:195], v[144:145], v[102:103], v[106:107]
	v_fmac_f32_dpp v188, v150, v80 row_shr:1 row_mask:0xf bank_mask:0xf
	v_fmac_f32_dpp v189, v151, v81 row_shr:1 row_mask:0xf bank_mask:0xf
	v_fmac_f32_dpp v190, v152, v82 row_shr:1 row_mask:0xf bank_mask:0xf
	v_fmac_f32_dpp v191, v153, v83 row_shr:1 row_mask:0xf bank_mask:0xf
	v_fmac_f32_dpp v192, v142, v96 row_shr:1 row_mask:0xf bank_mask:0xf
	v_fmac_f32_dpp v193, v143, v97 row_shr:1 row_mask:0xf bank_mask:0xf
	v_fmac_f32_dpp v194, v144, v98 row_shr:1 row_mask:0xf bank_mask:0xf
	v_fmac_f32_dpp v195, v145, v99 row_shr:1 row_mask:0xf bank_mask:0xf
	v_fmac_f32_dpp v188, v150, v76 row_shr:2 row_mask:0xf bank_mask:0xf
	v_fmac_f32_dpp v189, v151, v77 row_shr:2 row_mask:0xf bank_mask:0xf
	v_fmac_f32_dpp v190, v152, v78 row_shr:2 row_mask:0xf bank_mask:0xf
	v_fmac_f32_dpp v191, v153, v79 row_shr:2 row_mask:0xf bank_mask:0xf
	v_fmac_f32_dpp v192, v142, v92 row_shr:2 row_mask:0xf bank_mask:0xf
	v_fmac_f32_dpp v193, v143, v93 row_shr:2 row_mask:0xf bank_mask:0xf
	v_fmac_f32_dpp v194, v144, v94 row_shr:2 row_mask:0xf bank_mask:0xf
	v_fmac_f32_dpp v195, v145, v95 row_shr:2 row_mask:0xf bank_mask:0xf
	v_fmac_f32_dpp v188, v158, v80 row_shl:15 row_mask:0xf bank_mask:0xf
	v_fmac_f32_dpp v189, v159, v81 row_shl:15 row_mask:0xf bank_mask:0xf
	v_fmac_f32_dpp v190, v160, v82 row_shl:15 row_mask:0xf bank_mask:0xf
	v_fmac_f32_dpp v191, v161, v83 row_shl:15 row_mask:0xf bank_mask:0xf
	v_fmac_f32_dpp v192, v154, v96 row_shl:15 row_mask:0xf bank_mask:0xf
	v_fmac_f32_dpp v193, v155, v97 row_shl:15 row_mask:0xf bank_mask:0xf
	v_fmac_f32_dpp v194, v156, v98 row_shl:15 row_mask:0xf bank_mask:0xf
	v_fmac_f32_dpp v195, v157, v99 row_shl:15 row_mask:0xf bank_mask:0xf
	v_fmac_f32_dpp v188, v158, v76 row_shl:14 row_mask:0xf bank_mask:0xf
	v_fmac_f32_dpp v189, v159, v77 row_shl:14 row_mask:0xf bank_mask:0xf
	v_fmac_f32_dpp v190, v160, v78 row_shl:14 row_mask:0xf bank_mask:0xf
	v_fmac_f32_dpp v191, v161, v79 row_shl:14 row_mask:0xf bank_mask:0xf
	v_fmac_f32_dpp v192, v154, v92 row_shl:14 row_mask:0xf bank_mask:0xf
	v_fmac_f32_dpp v193, v155, v93 row_shl:14 row_mask:0xf bank_mask:0xf
	v_fmac_f32_dpp v194, v156, v94 row_shl:14 row_mask:0xf bank_mask:0xf
	v_fmac_f32_dpp v195, v157, v95 row_shl:14 row_mask:0xf bank_mask:0xf
	v_pk_mul_f32 v[196:197], v[188:189], v[216:217] op_sel_hi:[1,0]
	v_pk_mul_f32 v[198:199], v[190:191], v[216:217] op_sel_hi:[1,0]
	v_exp_f32_e32 v196, v196
	v_exp_f32_e32 v197, v197
	v_exp_f32_e32 v198, v198
	v_exp_f32_e32 v199, v199
	v_pk_add_f32 v[196:197], v[196:197], v[214:215] op_sel_hi:[1,0]
	v_pk_add_f32 v[198:199], v[198:199], v[214:215] op_sel_hi:[1,0]
	v_rcp_f32_e32 v196, v196
	v_rcp_f32_e32 v197, v197
	v_rcp_f32_e32 v198, v198
	v_rcp_f32_e32 v199, v199
	v_pk_mul_f32 v[188:189], v[188:189], v[196:197]
	v_pk_mul_f32 v[190:191], v[190:191], v[198:199]
	v_pk_mul_f32 v[188:189], v[188:189], v[192:193]
	v_pk_mul_f32 v[190:191], v[190:191], v[194:195]
	v_cvt_pk_bf16_f32 v158, v188, v189
	v_cvt_pk_bf16_f32 v159, v190, v191
	global_load_dwordx4 v[154:157], v212, s[82:83] offset:16
	v_pk_fma_f32 v[188:189], v[146:147], v[84:85], v[88:89]
	v_pk_fma_f32 v[190:191], v[148:149], v[86:87], v[90:91]
	v_pk_fma_f32 v[192:193], v[134:135], v[100:101], v[104:105]
	v_pk_fma_f32 v[194:195], v[136:137], v[102:103], v[106:107]
	v_fmac_f32_dpp v188, v146, v80 row_shr:1 row_mask:0xf bank_mask:0xf
	v_fmac_f32_dpp v189, v147, v81 row_shr:1 row_mask:0xf bank_mask:0xf
	v_fmac_f32_dpp v190, v148, v82 row_shr:1 row_mask:0xf bank_mask:0xf
	v_fmac_f32_dpp v191, v149, v83 row_shr:1 row_mask:0xf bank_mask:0xf
	v_fmac_f32_dpp v192, v134, v96 row_shr:1 row_mask:0xf bank_mask:0xf
	v_fmac_f32_dpp v193, v135, v97 row_shr:1 row_mask:0xf bank_mask:0xf
	v_fmac_f32_dpp v194, v136, v98 row_shr:1 row_mask:0xf bank_mask:0xf
	v_fmac_f32_dpp v195, v137, v99 row_shr:1 row_mask:0xf bank_mask:0xf
	v_fmac_f32_dpp v188, v146, v76 row_shr:2 row_mask:0xf bank_mask:0xf
	v_fmac_f32_dpp v189, v147, v77 row_shr:2 row_mask:0xf bank_mask:0xf
	v_fmac_f32_dpp v190, v148, v78 row_shr:2 row_mask:0xf bank_mask:0xf
	v_fmac_f32_dpp v191, v149, v79 row_shr:2 row_mask:0xf bank_mask:0xf
	v_fmac_f32_dpp v192, v134, v92 row_shr:2 row_mask:0xf bank_mask:0xf
	v_fmac_f32_dpp v193, v135, v93 row_shr:2 row_mask:0xf bank_mask:0xf
	v_fmac_f32_dpp v194, v136, v94 row_shr:2 row_mask:0xf bank_mask:0xf
	v_fmac_f32_dpp v195, v137, v95 row_shr:2 row_mask:0xf bank_mask:0xf
	v_fmac_f32_dpp v188, v150, v80 row_shl:15 row_mask:0xf bank_mask:0xf
	v_fmac_f32_dpp v189, v151, v81 row_shl:15 row_mask:0xf bank_mask:0xf
	v_fmac_f32_dpp v190, v152, v82 row_shl:15 row_mask:0xf bank_mask:0xf
	v_fmac_f32_dpp v191, v153, v83 row_shl:15 row_mask:0xf bank_mask:0xf
	v_fmac_f32_dpp v192, v142, v96 row_shl:15 row_mask:0xf bank_mask:0xf
	v_fmac_f32_dpp v193, v143, v97 row_shl:15 row_mask:0xf bank_mask:0xf
	v_fmac_f32_dpp v194, v144, v98 row_shl:15 row_mask:0xf bank_mask:0xf
	v_fmac_f32_dpp v195, v145, v99 row_shl:15 row_mask:0xf bank_mask:0xf
	v_fmac_f32_dpp v188, v150, v76 row_shl:14 row_mask:0xf bank_mask:0xf
	v_fmac_f32_dpp v189, v151, v77 row_shl:14 row_mask:0xf bank_mask:0xf
	v_fmac_f32_dpp v190, v152, v78 row_shl:14 row_mask:0xf bank_mask:0xf
	v_fmac_f32_dpp v191, v153, v79 row_shl:14 row_mask:0xf bank_mask:0xf
	v_fmac_f32_dpp v192, v142, v92 row_shl:14 row_mask:0xf bank_mask:0xf
	v_fmac_f32_dpp v193, v143, v93 row_shl:14 row_mask:0xf bank_mask:0xf
	v_fmac_f32_dpp v194, v144, v94 row_shl:14 row_mask:0xf bank_mask:0xf
	v_fmac_f32_dpp v195, v145, v95 row_shl:14 row_mask:0xf bank_mask:0xf
	v_pk_mul_f32 v[196:197], v[188:189], v[216:217] op_sel_hi:[1,0]
	v_pk_mul_f32 v[198:199], v[190:191], v[216:217] op_sel_hi:[1,0]
	v_exp_f32_e32 v196, v196
	v_exp_f32_e32 v197, v197
	v_exp_f32_e32 v198, v198
	v_exp_f32_e32 v199, v199
	v_pk_add_f32 v[196:197], v[196:197], v[214:215] op_sel_hi:[1,0]
	v_pk_add_f32 v[198:199], v[198:199], v[214:215] op_sel_hi:[1,0]
	v_rcp_f32_e32 v196, v196
	v_rcp_f32_e32 v197, v197
	v_rcp_f32_e32 v198, v198
	v_rcp_f32_e32 v199, v199
	v_pk_mul_f32 v[188:189], v[188:189], v[196:197]
	v_pk_mul_f32 v[190:191], v[190:191], v[198:199]
	v_pk_mul_f32 v[188:189], v[188:189], v[192:193]
	v_pk_mul_f32 v[190:191], v[190:191], v[194:195]
	v_cvt_pk_bf16_f32 v150, v188, v189
	v_cvt_pk_bf16_f32 v151, v190, v191
	v_add_u32_e32 v213, 0xb000, v212
	global_load_dwordx4 v[142:145], v213, s[82:83] offset:16
	v_pk_fma_f32 v[188:189], v[138:139], v[84:85], v[88:89]
	v_pk_fma_f32 v[190:191], v[140:141], v[86:87], v[90:91]
	v_pk_fma_f32 v[192:193], v[130:131], v[100:101], v[104:105]
	v_pk_fma_f32 v[194:195], v[132:133], v[102:103], v[106:107]
	v_fmac_f32_dpp v188, v138, v80 row_shr:1 row_mask:0xf bank_mask:0xf
	v_fmac_f32_dpp v189, v139, v81 row_shr:1 row_mask:0xf bank_mask:0xf
	v_fmac_f32_dpp v190, v140, v82 row_shr:1 row_mask:0xf bank_mask:0xf
	v_fmac_f32_dpp v191, v141, v83 row_shr:1 row_mask:0xf bank_mask:0xf
	v_fmac_f32_dpp v192, v130, v96 row_shr:1 row_mask:0xf bank_mask:0xf
	v_fmac_f32_dpp v193, v131, v97 row_shr:1 row_mask:0xf bank_mask:0xf
	v_fmac_f32_dpp v194, v132, v98 row_shr:1 row_mask:0xf bank_mask:0xf
	v_fmac_f32_dpp v195, v133, v99 row_shr:1 row_mask:0xf bank_mask:0xf
	v_fmac_f32_dpp v188, v138, v76 row_shr:2 row_mask:0xf bank_mask:0xf
	v_fmac_f32_dpp v189, v139, v77 row_shr:2 row_mask:0xf bank_mask:0xf
	v_fmac_f32_dpp v190, v140, v78 row_shr:2 row_mask:0xf bank_mask:0xf
	v_fmac_f32_dpp v191, v141, v79 row_shr:2 row_mask:0xf bank_mask:0xf
	v_fmac_f32_dpp v192, v130, v92 row_shr:2 row_mask:0xf bank_mask:0xf
	v_fmac_f32_dpp v193, v131, v93 row_shr:2 row_mask:0xf bank_mask:0xf
	v_fmac_f32_dpp v194, v132, v94 row_shr:2 row_mask:0xf bank_mask:0xf
	v_fmac_f32_dpp v195, v133, v95 row_shr:2 row_mask:0xf bank_mask:0xf
	v_fmac_f32_dpp v188, v146, v80 row_shl:15 row_mask:0xf bank_mask:0xf
	v_fmac_f32_dpp v189, v147, v81 row_shl:15 row_mask:0xf bank_mask:0xf
	v_fmac_f32_dpp v190, v148, v82 row_shl:15 row_mask:0xf bank_mask:0xf
	v_fmac_f32_dpp v191, v149, v83 row_shl:15 row_mask:0xf bank_mask:0xf
	v_fmac_f32_dpp v192, v134, v96 row_shl:15 row_mask:0xf bank_mask:0xf
	v_fmac_f32_dpp v193, v135, v97 row_shl:15 row_mask:0xf bank_mask:0xf
	v_fmac_f32_dpp v194, v136, v98 row_shl:15 row_mask:0xf bank_mask:0xf
	v_fmac_f32_dpp v195, v137, v99 row_shl:15 row_mask:0xf bank_mask:0xf
	v_fmac_f32_dpp v188, v146, v76 row_shl:14 row_mask:0xf bank_mask:0xf
	v_fmac_f32_dpp v189, v147, v77 row_shl:14 row_mask:0xf bank_mask:0xf
	v_fmac_f32_dpp v190, v148, v78 row_shl:14 row_mask:0xf bank_mask:0xf
	v_fmac_f32_dpp v191, v149, v79 row_shl:14 row_mask:0xf bank_mask:0xf
	v_fmac_f32_dpp v192, v134, v92 row_shl:14 row_mask:0xf bank_mask:0xf
	v_fmac_f32_dpp v193, v135, v93 row_shl:14 row_mask:0xf bank_mask:0xf
	v_fmac_f32_dpp v194, v136, v94 row_shl:14 row_mask:0xf bank_mask:0xf
	v_fmac_f32_dpp v195, v137, v95 row_shl:14 row_mask:0xf bank_mask:0xf
	v_pk_mul_f32 v[196:197], v[188:189], v[216:217] op_sel_hi:[1,0]
	v_pk_mul_f32 v[198:199], v[190:191], v[216:217] op_sel_hi:[1,0]
	v_exp_f32_e32 v196, v196
	v_exp_f32_e32 v197, v197
	v_exp_f32_e32 v198, v198
	v_exp_f32_e32 v199, v199
	v_pk_add_f32 v[196:197], v[196:197], v[214:215] op_sel_hi:[1,0]
	v_pk_add_f32 v[198:199], v[198:199], v[214:215] op_sel_hi:[1,0]
	v_rcp_f32_e32 v196, v196
	v_rcp_f32_e32 v197, v197
	v_rcp_f32_e32 v198, v198
	v_rcp_f32_e32 v199, v199
	v_pk_mul_f32 v[188:189], v[188:189], v[196:197]
	v_pk_mul_f32 v[190:191], v[190:191], v[198:199]
	v_pk_mul_f32 v[188:189], v[188:189], v[192:193]
	v_pk_mul_f32 v[190:191], v[190:191], v[194:195]
	v_cvt_pk_bf16_f32 v146, v188, v189
	v_cvt_pk_bf16_f32 v147, v190, v191
	v_add_u32_e32 v213, 0x16000, v212
	global_load_dwordx4 v[134:137], v213, s[82:83] offset:16
	v_pk_fma_f32 v[188:189], v[126:127], v[84:85], v[88:89]
	v_pk_fma_f32 v[190:191], v[128:129], v[86:87], v[90:91]
	v_pk_fma_f32 v[192:193], v[118:119], v[100:101], v[104:105]
	v_pk_fma_f32 v[194:195], v[120:121], v[102:103], v[106:107]
	v_fmac_f32_dpp v188, v126, v80 row_shr:1 row_mask:0xf bank_mask:0xf
	v_fmac_f32_dpp v189, v127, v81 row_shr:1 row_mask:0xf bank_mask:0xf
	v_fmac_f32_dpp v190, v128, v82 row_shr:1 row_mask:0xf bank_mask:0xf
	v_fmac_f32_dpp v191, v129, v83 row_shr:1 row_mask:0xf bank_mask:0xf
	v_fmac_f32_dpp v192, v118, v96 row_shr:1 row_mask:0xf bank_mask:0xf
	v_fmac_f32_dpp v193, v119, v97 row_shr:1 row_mask:0xf bank_mask:0xf
	v_fmac_f32_dpp v194, v120, v98 row_shr:1 row_mask:0xf bank_mask:0xf
	v_fmac_f32_dpp v195, v121, v99 row_shr:1 row_mask:0xf bank_mask:0xf
	v_fmac_f32_dpp v188, v126, v76 row_shr:2 row_mask:0xf bank_mask:0xf
	v_fmac_f32_dpp v189, v127, v77 row_shr:2 row_mask:0xf bank_mask:0xf
	v_fmac_f32_dpp v190, v128, v78 row_shr:2 row_mask:0xf bank_mask:0xf
	v_fmac_f32_dpp v191, v129, v79 row_shr:2 row_mask:0xf bank_mask:0xf
	v_fmac_f32_dpp v192, v118, v92 row_shr:2 row_mask:0xf bank_mask:0xf
	v_fmac_f32_dpp v193, v119, v93 row_shr:2 row_mask:0xf bank_mask:0xf
	v_fmac_f32_dpp v194, v120, v94 row_shr:2 row_mask:0xf bank_mask:0xf
	v_fmac_f32_dpp v195, v121, v95 row_shr:2 row_mask:0xf bank_mask:0xf
	v_fmac_f32_dpp v188, v138, v80 row_shl:15 row_mask:0xf bank_mask:0xf
	v_fmac_f32_dpp v189, v139, v81 row_shl:15 row_mask:0xf bank_mask:0xf
	v_fmac_f32_dpp v190, v140, v82 row_shl:15 row_mask:0xf bank_mask:0xf
	v_fmac_f32_dpp v191, v141, v83 row_shl:15 row_mask:0xf bank_mask:0xf
	v_fmac_f32_dpp v192, v130, v96 row_shl:15 row_mask:0xf bank_mask:0xf
	v_fmac_f32_dpp v193, v131, v97 row_shl:15 row_mask:0xf bank_mask:0xf
	v_fmac_f32_dpp v194, v132, v98 row_shl:15 row_mask:0xf bank_mask:0xf
	v_fmac_f32_dpp v195, v133, v99 row_shl:15 row_mask:0xf bank_mask:0xf
	v_fmac_f32_dpp v188, v138, v76 row_shl:14 row_mask:0xf bank_mask:0xf
	v_fmac_f32_dpp v189, v139, v77 row_shl:14 row_mask:0xf bank_mask:0xf
	v_fmac_f32_dpp v190, v140, v78 row_shl:14 row_mask:0xf bank_mask:0xf
	v_fmac_f32_dpp v191, v141, v79 row_shl:14 row_mask:0xf bank_mask:0xf
	v_fmac_f32_dpp v192, v130, v92 row_shl:14 row_mask:0xf bank_mask:0xf
	v_fmac_f32_dpp v193, v131, v93 row_shl:14 row_mask:0xf bank_mask:0xf
	v_fmac_f32_dpp v194, v132, v94 row_shl:14 row_mask:0xf bank_mask:0xf
	v_fmac_f32_dpp v195, v133, v95 row_shl:14 row_mask:0xf bank_mask:0xf
	v_pk_mul_f32 v[196:197], v[188:189], v[216:217] op_sel_hi:[1,0]
	v_pk_mul_f32 v[198:199], v[190:191], v[216:217] op_sel_hi:[1,0]
	v_exp_f32_e32 v196, v196
	v_exp_f32_e32 v197, v197
	v_exp_f32_e32 v198, v198
	v_exp_f32_e32 v199, v199
	v_pk_add_f32 v[196:197], v[196:197], v[214:215] op_sel_hi:[1,0]
	v_pk_add_f32 v[198:199], v[198:199], v[214:215] op_sel_hi:[1,0]
	v_rcp_f32_e32 v196, v196
	v_rcp_f32_e32 v197, v197
	v_rcp_f32_e32 v198, v198
	v_rcp_f32_e32 v199, v199
	v_pk_mul_f32 v[188:189], v[188:189], v[196:197]
	v_pk_mul_f32 v[190:191], v[190:191], v[198:199]
	v_pk_mul_f32 v[188:189], v[188:189], v[192:193]
	v_pk_mul_f32 v[190:191], v[190:191], v[194:195]
	v_cvt_pk_bf16_f32 v138, v188, v189
	v_cvt_pk_bf16_f32 v139, v190, v191
	global_load_dwordx4 v[130:133], v212, s[84:85] offset:16
	v_pk_fma_f32 v[188:189], v[122:123], v[84:85], v[88:89]
	v_pk_fma_f32 v[190:191], v[124:125], v[86:87], v[90:91]
	v_pk_fma_f32 v[192:193], v[110:111], v[100:101], v[104:105]
	v_pk_fma_f32 v[194:195], v[112:113], v[102:103], v[106:107]
	v_fmac_f32_dpp v188, v122, v80 row_shr:1 row_mask:0xf bank_mask:0xf
	v_fmac_f32_dpp v189, v123, v81 row_shr:1 row_mask:0xf bank_mask:0xf
	v_fmac_f32_dpp v190, v124, v82 row_shr:1 row_mask:0xf bank_mask:0xf
	v_fmac_f32_dpp v191, v125, v83 row_shr:1 row_mask:0xf bank_mask:0xf
	v_fmac_f32_dpp v192, v110, v96 row_shr:1 row_mask:0xf bank_mask:0xf
	v_fmac_f32_dpp v193, v111, v97 row_shr:1 row_mask:0xf bank_mask:0xf
	v_fmac_f32_dpp v194, v112, v98 row_shr:1 row_mask:0xf bank_mask:0xf
	v_fmac_f32_dpp v195, v113, v99 row_shr:1 row_mask:0xf bank_mask:0xf
	v_fmac_f32_dpp v188, v122, v76 row_shr:2 row_mask:0xf bank_mask:0xf
	v_fmac_f32_dpp v189, v123, v77 row_shr:2 row_mask:0xf bank_mask:0xf
	v_fmac_f32_dpp v190, v124, v78 row_shr:2 row_mask:0xf bank_mask:0xf
	v_fmac_f32_dpp v191, v125, v79 row_shr:2 row_mask:0xf bank_mask:0xf
	v_fmac_f32_dpp v192, v110, v92 row_shr:2 row_mask:0xf bank_mask:0xf
	v_fmac_f32_dpp v193, v111, v93 row_shr:2 row_mask:0xf bank_mask:0xf
	v_fmac_f32_dpp v194, v112, v94 row_shr:2 row_mask:0xf bank_mask:0xf
	v_fmac_f32_dpp v195, v113, v95 row_shr:2 row_mask:0xf bank_mask:0xf
	v_fmac_f32_dpp v188, v126, v80 row_shl:15 row_mask:0xf bank_mask:0xf
	v_fmac_f32_dpp v189, v127, v81 row_shl:15 row_mask:0xf bank_mask:0xf
	v_fmac_f32_dpp v190, v128, v82 row_shl:15 row_mask:0xf bank_mask:0xf
	v_fmac_f32_dpp v191, v129, v83 row_shl:15 row_mask:0xf bank_mask:0xf
	v_fmac_f32_dpp v192, v118, v96 row_shl:15 row_mask:0xf bank_mask:0xf
	v_fmac_f32_dpp v193, v119, v97 row_shl:15 row_mask:0xf bank_mask:0xf
	v_fmac_f32_dpp v194, v120, v98 row_shl:15 row_mask:0xf bank_mask:0xf
	v_fmac_f32_dpp v195, v121, v99 row_shl:15 row_mask:0xf bank_mask:0xf
	v_fmac_f32_dpp v188, v126, v76 row_shl:14 row_mask:0xf bank_mask:0xf
	v_fmac_f32_dpp v189, v127, v77 row_shl:14 row_mask:0xf bank_mask:0xf
	v_fmac_f32_dpp v190, v128, v78 row_shl:14 row_mask:0xf bank_mask:0xf
	v_fmac_f32_dpp v191, v129, v79 row_shl:14 row_mask:0xf bank_mask:0xf
	v_fmac_f32_dpp v192, v118, v92 row_shl:14 row_mask:0xf bank_mask:0xf
	v_fmac_f32_dpp v193, v119, v93 row_shl:14 row_mask:0xf bank_mask:0xf
	v_fmac_f32_dpp v194, v120, v94 row_shl:14 row_mask:0xf bank_mask:0xf
	v_fmac_f32_dpp v195, v121, v95 row_shl:14 row_mask:0xf bank_mask:0xf
	v_pk_mul_f32 v[196:197], v[188:189], v[216:217] op_sel_hi:[1,0]
	v_pk_mul_f32 v[198:199], v[190:191], v[216:217] op_sel_hi:[1,0]
	v_exp_f32_e32 v196, v196
	v_exp_f32_e32 v197, v197
	v_exp_f32_e32 v198, v198
	v_exp_f32_e32 v199, v199
	v_pk_add_f32 v[196:197], v[196:197], v[214:215] op_sel_hi:[1,0]
	v_pk_add_f32 v[198:199], v[198:199], v[214:215] op_sel_hi:[1,0]
	v_rcp_f32_e32 v196, v196
	v_rcp_f32_e32 v197, v197
	v_rcp_f32_e32 v198, v198
	v_rcp_f32_e32 v199, v199
	v_pk_mul_f32 v[188:189], v[188:189], v[196:197]
	v_pk_mul_f32 v[190:191], v[190:191], v[198:199]
	v_pk_mul_f32 v[188:189], v[188:189], v[192:193]
	v_pk_mul_f32 v[190:191], v[190:191], v[194:195]
	v_cvt_pk_bf16_f32 v126, v188, v189
	v_cvt_pk_bf16_f32 v127, v190, v191
	v_add_u32_e32 v213, 0x5800, v212
	global_load_dwordx4 v[118:121], v213, s[82:83] offset:16
	v_pk_fma_f32 v[188:189], v[114:115], v[84:85], v[88:89]
	v_pk_fma_f32 v[190:191], v[116:117], v[86:87], v[90:91]
	v_pk_fma_f32 v[192:193], v[68:69], v[100:101], v[104:105]
	v_pk_fma_f32 v[194:195], v[70:71], v[102:103], v[106:107]
	v_fmac_f32_dpp v188, v114, v80 row_shr:1 row_mask:0xf bank_mask:0xf
	v_fmac_f32_dpp v189, v115, v81 row_shr:1 row_mask:0xf bank_mask:0xf
	v_fmac_f32_dpp v190, v116, v82 row_shr:1 row_mask:0xf bank_mask:0xf
	v_fmac_f32_dpp v191, v117, v83 row_shr:1 row_mask:0xf bank_mask:0xf
	v_fmac_f32_dpp v192, v68, v96 row_shr:1 row_mask:0xf bank_mask:0xf
	v_fmac_f32_dpp v193, v69, v97 row_shr:1 row_mask:0xf bank_mask:0xf
	v_fmac_f32_dpp v194, v70, v98 row_shr:1 row_mask:0xf bank_mask:0xf
	v_fmac_f32_dpp v195, v71, v99 row_shr:1 row_mask:0xf bank_mask:0xf
	v_fmac_f32_dpp v188, v114, v76 row_shr:2 row_mask:0xf bank_mask:0xf
	v_fmac_f32_dpp v189, v115, v77 row_shr:2 row_mask:0xf bank_mask:0xf
	v_fmac_f32_dpp v190, v116, v78 row_shr:2 row_mask:0xf bank_mask:0xf
	v_fmac_f32_dpp v191, v117, v79 row_shr:2 row_mask:0xf bank_mask:0xf
	v_fmac_f32_dpp v192, v68, v92 row_shr:2 row_mask:0xf bank_mask:0xf
	v_fmac_f32_dpp v193, v69, v93 row_shr:2 row_mask:0xf bank_mask:0xf
	v_fmac_f32_dpp v194, v70, v94 row_shr:2 row_mask:0xf bank_mask:0xf
	v_fmac_f32_dpp v195, v71, v95 row_shr:2 row_mask:0xf bank_mask:0xf
	v_fmac_f32_dpp v188, v122, v80 row_shl:15 row_mask:0xf bank_mask:0xf
	v_fmac_f32_dpp v189, v123, v81 row_shl:15 row_mask:0xf bank_mask:0xf
	v_fmac_f32_dpp v190, v124, v82 row_shl:15 row_mask:0xf bank_mask:0xf
	v_fmac_f32_dpp v191, v125, v83 row_shl:15 row_mask:0xf bank_mask:0xf
	v_fmac_f32_dpp v192, v110, v96 row_shl:15 row_mask:0xf bank_mask:0xf
	v_fmac_f32_dpp v193, v111, v97 row_shl:15 row_mask:0xf bank_mask:0xf
	v_fmac_f32_dpp v194, v112, v98 row_shl:15 row_mask:0xf bank_mask:0xf
	v_fmac_f32_dpp v195, v113, v99 row_shl:15 row_mask:0xf bank_mask:0xf
	v_fmac_f32_dpp v188, v122, v76 row_shl:14 row_mask:0xf bank_mask:0xf
	v_fmac_f32_dpp v189, v123, v77 row_shl:14 row_mask:0xf bank_mask:0xf
	v_fmac_f32_dpp v190, v124, v78 row_shl:14 row_mask:0xf bank_mask:0xf
	v_fmac_f32_dpp v191, v125, v79 row_shl:14 row_mask:0xf bank_mask:0xf
	v_fmac_f32_dpp v192, v110, v92 row_shl:14 row_mask:0xf bank_mask:0xf
	v_fmac_f32_dpp v193, v111, v93 row_shl:14 row_mask:0xf bank_mask:0xf
	v_fmac_f32_dpp v194, v112, v94 row_shl:14 row_mask:0xf bank_mask:0xf
	v_fmac_f32_dpp v195, v113, v95 row_shl:14 row_mask:0xf bank_mask:0xf
	v_pk_mul_f32 v[196:197], v[188:189], v[216:217] op_sel_hi:[1,0]
	v_pk_mul_f32 v[198:199], v[190:191], v[216:217] op_sel_hi:[1,0]
	v_exp_f32_e32 v196, v196
	v_exp_f32_e32 v197, v197
	v_exp_f32_e32 v198, v198
	v_exp_f32_e32 v199, v199
	v_pk_add_f32 v[196:197], v[196:197], v[214:215] op_sel_hi:[1,0]
	v_pk_add_f32 v[198:199], v[198:199], v[214:215] op_sel_hi:[1,0]
	v_rcp_f32_e32 v196, v196
	v_rcp_f32_e32 v197, v197
	v_rcp_f32_e32 v198, v198
	v_rcp_f32_e32 v199, v199
	v_pk_mul_f32 v[188:189], v[188:189], v[196:197]
	v_pk_mul_f32 v[190:191], v[190:191], v[198:199]
	v_pk_mul_f32 v[188:189], v[188:189], v[192:193]
	v_pk_mul_f32 v[190:191], v[190:191], v[194:195]
	v_cvt_pk_bf16_f32 v122, v188, v189
	v_cvt_pk_bf16_f32 v123, v190, v191
	v_add_u32_e32 v213, 0x10800, v212
	global_load_dwordx4 v[110:113], v213, s[82:83] offset:16
	v_pk_fma_f32 v[188:189], v[72:73], v[84:85], v[88:89]
	v_pk_fma_f32 v[190:191], v[74:75], v[86:87], v[90:91]
	v_pk_fma_f32 v[192:193], v[64:65], v[100:101], v[104:105]
	v_pk_fma_f32 v[194:195], v[66:67], v[102:103], v[106:107]
	v_fmac_f32_dpp v188, v72, v80 row_shr:1 row_mask:0xf bank_mask:0xf
	v_fmac_f32_dpp v189, v73, v81 row_shr:1 row_mask:0xf bank_mask:0xf
	v_fmac_f32_dpp v190, v74, v82 row_shr:1 row_mask:0xf bank_mask:0xf
	v_fmac_f32_dpp v191, v75, v83 row_shr:1 row_mask:0xf bank_mask:0xf
	v_fmac_f32_dpp v192, v64, v96 row_shr:1 row_mask:0xf bank_mask:0xf
	v_fmac_f32_dpp v193, v65, v97 row_shr:1 row_mask:0xf bank_mask:0xf
	v_fmac_f32_dpp v194, v66, v98 row_shr:1 row_mask:0xf bank_mask:0xf
	v_fmac_f32_dpp v195, v67, v99 row_shr:1 row_mask:0xf bank_mask:0xf
	v_fmac_f32_dpp v188, v72, v76 row_shr:2 row_mask:0xf bank_mask:0xf
	v_fmac_f32_dpp v189, v73, v77 row_shr:2 row_mask:0xf bank_mask:0xf
	v_fmac_f32_dpp v190, v74, v78 row_shr:2 row_mask:0xf bank_mask:0xf
	v_fmac_f32_dpp v191, v75, v79 row_shr:2 row_mask:0xf bank_mask:0xf
	v_fmac_f32_dpp v192, v64, v92 row_shr:2 row_mask:0xf bank_mask:0xf
	v_fmac_f32_dpp v193, v65, v93 row_shr:2 row_mask:0xf bank_mask:0xf
	v_fmac_f32_dpp v194, v66, v94 row_shr:2 row_mask:0xf bank_mask:0xf
	v_fmac_f32_dpp v195, v67, v95 row_shr:2 row_mask:0xf bank_mask:0xf
	v_fmac_f32_dpp v188, v114, v80 row_shl:15 row_mask:0xf bank_mask:0xf
	v_fmac_f32_dpp v189, v115, v81 row_shl:15 row_mask:0xf bank_mask:0xf
	v_fmac_f32_dpp v190, v116, v82 row_shl:15 row_mask:0xf bank_mask:0xf
	v_fmac_f32_dpp v191, v117, v83 row_shl:15 row_mask:0xf bank_mask:0xf
	v_fmac_f32_dpp v192, v68, v96 row_shl:15 row_mask:0xf bank_mask:0xf
	v_fmac_f32_dpp v193, v69, v97 row_shl:15 row_mask:0xf bank_mask:0xf
	v_fmac_f32_dpp v194, v70, v98 row_shl:15 row_mask:0xf bank_mask:0xf
	v_fmac_f32_dpp v195, v71, v99 row_shl:15 row_mask:0xf bank_mask:0xf
	v_fmac_f32_dpp v188, v114, v76 row_shl:14 row_mask:0xf bank_mask:0xf
	v_fmac_f32_dpp v189, v115, v77 row_shl:14 row_mask:0xf bank_mask:0xf
	v_fmac_f32_dpp v190, v116, v78 row_shl:14 row_mask:0xf bank_mask:0xf
	v_fmac_f32_dpp v191, v117, v79 row_shl:14 row_mask:0xf bank_mask:0xf
	v_fmac_f32_dpp v192, v68, v92 row_shl:14 row_mask:0xf bank_mask:0xf
	v_fmac_f32_dpp v193, v69, v93 row_shl:14 row_mask:0xf bank_mask:0xf
	v_fmac_f32_dpp v194, v70, v94 row_shl:14 row_mask:0xf bank_mask:0xf
	v_fmac_f32_dpp v195, v71, v95 row_shl:14 row_mask:0xf bank_mask:0xf
	v_pk_mul_f32 v[196:197], v[188:189], v[216:217] op_sel_hi:[1,0]
	v_pk_mul_f32 v[198:199], v[190:191], v[216:217] op_sel_hi:[1,0]
	v_exp_f32_e32 v196, v196
	v_exp_f32_e32 v197, v197
	v_exp_f32_e32 v198, v198
	v_exp_f32_e32 v199, v199
	v_pk_add_f32 v[196:197], v[196:197], v[214:215] op_sel_hi:[1,0]
	v_pk_add_f32 v[198:199], v[198:199], v[214:215] op_sel_hi:[1,0]
	v_rcp_f32_e32 v196, v196
	v_rcp_f32_e32 v197, v197
	v_rcp_f32_e32 v198, v198
	v_rcp_f32_e32 v199, v199
	v_pk_mul_f32 v[188:189], v[188:189], v[196:197]
	v_pk_mul_f32 v[190:191], v[190:191], v[198:199]
	v_pk_mul_f32 v[188:189], v[188:189], v[192:193]
	v_pk_mul_f32 v[190:191], v[190:191], v[194:195]
	v_cvt_pk_bf16_f32 v114, v188, v189
	v_cvt_pk_bf16_f32 v115, v190, v191
	s_waitcnt vmcnt(0)
	v_pk_fma_f32 v[188:189], v[60:61], v[134:135], v[130:131]
	v_pk_fma_f32 v[190:191], v[62:63], v[136:137], v[132:133]
	v_pk_fma_f32 v[192:193], v[56:57], v[204:205], v[208:209]
	v_pk_fma_f32 v[194:195], v[58:59], v[206:207], v[210:211]
	v_fmac_f32_dpp v188, v60, v142 row_shr:1 row_mask:0xf bank_mask:0xf
	v_fmac_f32_dpp v189, v61, v143 row_shr:1 row_mask:0xf bank_mask:0xf
	v_fmac_f32_dpp v190, v62, v144 row_shr:1 row_mask:0xf bank_mask:0xf
	v_fmac_f32_dpp v191, v63, v145 row_shr:1 row_mask:0xf bank_mask:0xf
	v_fmac_f32_dpp v192, v56, v110 row_shr:1 row_mask:0xf bank_mask:0xf
	v_fmac_f32_dpp v193, v57, v111 row_shr:1 row_mask:0xf bank_mask:0xf
	v_fmac_f32_dpp v194, v58, v112 row_shr:1 row_mask:0xf bank_mask:0xf
	v_fmac_f32_dpp v195, v59, v113 row_shr:1 row_mask:0xf bank_mask:0xf
	v_fmac_f32_dpp v188, v60, v154 row_shr:2 row_mask:0xf bank_mask:0xf
	v_fmac_f32_dpp v189, v61, v155 row_shr:2 row_mask:0xf bank_mask:0xf
	v_fmac_f32_dpp v190, v62, v156 row_shr:2 row_mask:0xf bank_mask:0xf
	v_fmac_f32_dpp v191, v63, v157 row_shr:2 row_mask:0xf bank_mask:0xf
	v_fmac_f32_dpp v192, v56, v118 row_shr:2 row_mask:0xf bank_mask:0xf
	v_fmac_f32_dpp v193, v57, v119 row_shr:2 row_mask:0xf bank_mask:0xf
	v_fmac_f32_dpp v194, v58, v120 row_shr:2 row_mask:0xf bank_mask:0xf
	v_fmac_f32_dpp v195, v59, v121 row_shr:2 row_mask:0xf bank_mask:0xf
	v_pk_mul_f32 v[196:197], v[188:189], v[216:217] op_sel_hi:[1,0]
	v_pk_mul_f32 v[198:199], v[190:191], v[216:217] op_sel_hi:[1,0]
	v_exp_f32_e32 v196, v196
	v_exp_f32_e32 v197, v197
	v_exp_f32_e32 v198, v198
	v_exp_f32_e32 v199, v199
	v_pk_add_f32 v[196:197], v[196:197], v[214:215] op_sel_hi:[1,0]
	v_pk_add_f32 v[198:199], v[198:199], v[214:215] op_sel_hi:[1,0]
	v_rcp_f32_e32 v196, v196
	v_rcp_f32_e32 v197, v197
	v_rcp_f32_e32 v198, v198
	v_rcp_f32_e32 v199, v199
	v_pk_mul_f32 v[188:189], v[188:189], v[196:197]
	v_pk_mul_f32 v[190:191], v[190:191], v[198:199]
	v_pk_mul_f32 v[188:189], v[188:189], v[192:193]
	v_pk_mul_f32 v[190:191], v[190:191], v[194:195]
	v_cvt_pk_bf16_f32 v202, v188, v189
	v_cvt_pk_bf16_f32 v203, v190, v191
	s_mov_b64 exec, vcc
	global_store_dwordx4 v215, v[200:203], s[96:97] nt
	s_mov_b64 exec, -1
	v_pk_fma_f32 v[188:189], v[52:53], v[134:135], v[130:131]
	v_pk_fma_f32 v[190:191], v[54:55], v[136:137], v[132:133]
	v_pk_fma_f32 v[192:193], v[44:45], v[204:205], v[208:209]
	v_pk_fma_f32 v[194:195], v[46:47], v[206:207], v[210:211]
	v_fmac_f32_dpp v188, v52, v142 row_shr:1 row_mask:0xf bank_mask:0xf
	v_fmac_f32_dpp v189, v53, v143 row_shr:1 row_mask:0xf bank_mask:0xf
	v_fmac_f32_dpp v190, v54, v144 row_shr:1 row_mask:0xf bank_mask:0xf
	v_fmac_f32_dpp v191, v55, v145 row_shr:1 row_mask:0xf bank_mask:0xf
	v_fmac_f32_dpp v192, v44, v110 row_shr:1 row_mask:0xf bank_mask:0xf
	v_fmac_f32_dpp v193, v45, v111 row_shr:1 row_mask:0xf bank_mask:0xf
	v_fmac_f32_dpp v194, v46, v112 row_shr:1 row_mask:0xf bank_mask:0xf
	v_fmac_f32_dpp v195, v47, v113 row_shr:1 row_mask:0xf bank_mask:0xf
	v_fmac_f32_dpp v188, v52, v154 row_shr:2 row_mask:0xf bank_mask:0xf
	v_fmac_f32_dpp v189, v53, v155 row_shr:2 row_mask:0xf bank_mask:0xf
	v_fmac_f32_dpp v190, v54, v156 row_shr:2 row_mask:0xf bank_mask:0xf
	v_fmac_f32_dpp v191, v55, v157 row_shr:2 row_mask:0xf bank_mask:0xf
	v_fmac_f32_dpp v192, v44, v118 row_shr:2 row_mask:0xf bank_mask:0xf
	v_fmac_f32_dpp v193, v45, v119 row_shr:2 row_mask:0xf bank_mask:0xf
	v_fmac_f32_dpp v194, v46, v120 row_shr:2 row_mask:0xf bank_mask:0xf
	v_fmac_f32_dpp v195, v47, v121 row_shr:2 row_mask:0xf bank_mask:0xf
	v_fmac_f32_dpp v188, v60, v142 row_shl:15 row_mask:0xf bank_mask:0xf
	v_fmac_f32_dpp v189, v61, v143 row_shl:15 row_mask:0xf bank_mask:0xf
	v_fmac_f32_dpp v190, v62, v144 row_shl:15 row_mask:0xf bank_mask:0xf
	v_fmac_f32_dpp v191, v63, v145 row_shl:15 row_mask:0xf bank_mask:0xf
	v_fmac_f32_dpp v192, v56, v110 row_shl:15 row_mask:0xf bank_mask:0xf
	v_fmac_f32_dpp v193, v57, v111 row_shl:15 row_mask:0xf bank_mask:0xf
	v_fmac_f32_dpp v194, v58, v112 row_shl:15 row_mask:0xf bank_mask:0xf
	v_fmac_f32_dpp v195, v59, v113 row_shl:15 row_mask:0xf bank_mask:0xf
	v_fmac_f32_dpp v188, v60, v154 row_shl:14 row_mask:0xf bank_mask:0xf
	v_fmac_f32_dpp v189, v61, v155 row_shl:14 row_mask:0xf bank_mask:0xf
	v_fmac_f32_dpp v190, v62, v156 row_shl:14 row_mask:0xf bank_mask:0xf
	v_fmac_f32_dpp v191, v63, v157 row_shl:14 row_mask:0xf bank_mask:0xf
	v_fmac_f32_dpp v192, v56, v118 row_shl:14 row_mask:0xf bank_mask:0xf
	v_fmac_f32_dpp v193, v57, v119 row_shl:14 row_mask:0xf bank_mask:0xf
	v_fmac_f32_dpp v194, v58, v120 row_shl:14 row_mask:0xf bank_mask:0xf
	v_fmac_f32_dpp v195, v59, v121 row_shl:14 row_mask:0xf bank_mask:0xf
	v_pk_mul_f32 v[196:197], v[188:189], v[216:217] op_sel_hi:[1,0]
	v_pk_mul_f32 v[198:199], v[190:191], v[216:217] op_sel_hi:[1,0]
	v_exp_f32_e32 v196, v196
	v_exp_f32_e32 v197, v197
	v_exp_f32_e32 v198, v198
	v_exp_f32_e32 v199, v199
	v_pk_add_f32 v[196:197], v[196:197], v[214:215] op_sel_hi:[1,0]
	v_pk_add_f32 v[198:199], v[198:199], v[214:215] op_sel_hi:[1,0]
	v_rcp_f32_e32 v196, v196
	v_rcp_f32_e32 v197, v197
	v_rcp_f32_e32 v198, v198
	v_rcp_f32_e32 v199, v199
	v_pk_mul_f32 v[188:189], v[188:189], v[196:197]
	v_pk_mul_f32 v[190:191], v[190:191], v[198:199]
	v_pk_mul_f32 v[188:189], v[188:189], v[192:193]
	v_pk_mul_f32 v[190:191], v[190:191], v[194:195]
	v_cvt_pk_bf16_f32 v160, v188, v189
	v_cvt_pk_bf16_f32 v161, v190, v191
	v_add_u32_e32 v213, 0x2c000, v215
	global_store_dwordx4 v213, v[158:161], s[96:97] nt
	v_pk_fma_f32 v[188:189], v[48:49], v[134:135], v[130:131]
	v_pk_fma_f32 v[190:191], v[50:51], v[136:137], v[132:133]
	v_pk_fma_f32 v[192:193], v[36:37], v[204:205], v[208:209]
	v_pk_fma_f32 v[194:195], v[38:39], v[206:207], v[210:211]
	v_fmac_f32_dpp v188, v48, v142 row_shr:1 row_mask:0xf bank_mask:0xf
	v_fmac_f32_dpp v189, v49, v143 row_shr:1 row_mask:0xf bank_mask:0xf
	v_fmac_f32_dpp v190, v50, v144 row_shr:1 row_mask:0xf bank_mask:0xf
	v_fmac_f32_dpp v191, v51, v145 row_shr:1 row_mask:0xf bank_mask:0xf
	v_fmac_f32_dpp v192, v36, v110 row_shr:1 row_mask:0xf bank_mask:0xf
	v_fmac_f32_dpp v193, v37, v111 row_shr:1 row_mask:0xf bank_mask:0xf
	v_fmac_f32_dpp v194, v38, v112 row_shr:1 row_mask:0xf bank_mask:0xf
	v_fmac_f32_dpp v195, v39, v113 row_shr:1 row_mask:0xf bank_mask:0xf
	v_fmac_f32_dpp v188, v48, v154 row_shr:2 row_mask:0xf bank_mask:0xf
	v_fmac_f32_dpp v189, v49, v155 row_shr:2 row_mask:0xf bank_mask:0xf
	v_fmac_f32_dpp v190, v50, v156 row_shr:2 row_mask:0xf bank_mask:0xf
	v_fmac_f32_dpp v191, v51, v157 row_shr:2 row_mask:0xf bank_mask:0xf
	v_fmac_f32_dpp v192, v36, v118 row_shr:2 row_mask:0xf bank_mask:0xf
	v_fmac_f32_dpp v193, v37, v119 row_shr:2 row_mask:0xf bank_mask:0xf
	v_fmac_f32_dpp v194, v38, v120 row_shr:2 row_mask:0xf bank_mask:0xf
	v_fmac_f32_dpp v195, v39, v121 row_shr:2 row_mask:0xf bank_mask:0xf
	v_fmac_f32_dpp v188, v52, v142 row_shl:15 row_mask:0xf bank_mask:0xf
	v_fmac_f32_dpp v189, v53, v143 row_shl:15 row_mask:0xf bank_mask:0xf
	v_fmac_f32_dpp v190, v54, v144 row_shl:15 row_mask:0xf bank_mask:0xf
	v_fmac_f32_dpp v191, v55, v145 row_shl:15 row_mask:0xf bank_mask:0xf
	v_fmac_f32_dpp v192, v44, v110 row_shl:15 row_mask:0xf bank_mask:0xf
	v_fmac_f32_dpp v193, v45, v111 row_shl:15 row_mask:0xf bank_mask:0xf
	v_fmac_f32_dpp v194, v46, v112 row_shl:15 row_mask:0xf bank_mask:0xf
	v_fmac_f32_dpp v195, v47, v113 row_shl:15 row_mask:0xf bank_mask:0xf
	v_fmac_f32_dpp v188, v52, v154 row_shl:14 row_mask:0xf bank_mask:0xf
	v_fmac_f32_dpp v189, v53, v155 row_shl:14 row_mask:0xf bank_mask:0xf
	v_fmac_f32_dpp v190, v54, v156 row_shl:14 row_mask:0xf bank_mask:0xf
	v_fmac_f32_dpp v191, v55, v157 row_shl:14 row_mask:0xf bank_mask:0xf
	v_fmac_f32_dpp v192, v44, v118 row_shl:14 row_mask:0xf bank_mask:0xf
	v_fmac_f32_dpp v193, v45, v119 row_shl:14 row_mask:0xf bank_mask:0xf
	v_fmac_f32_dpp v194, v46, v120 row_shl:14 row_mask:0xf bank_mask:0xf
	v_fmac_f32_dpp v195, v47, v121 row_shl:14 row_mask:0xf bank_mask:0xf
	v_pk_mul_f32 v[196:197], v[188:189], v[216:217] op_sel_hi:[1,0]
	v_pk_mul_f32 v[198:199], v[190:191], v[216:217] op_sel_hi:[1,0]
	v_exp_f32_e32 v196, v196
	v_exp_f32_e32 v197, v197
	v_exp_f32_e32 v198, v198
	v_exp_f32_e32 v199, v199
	v_pk_add_f32 v[196:197], v[196:197], v[214:215] op_sel_hi:[1,0]
	v_pk_add_f32 v[198:199], v[198:199], v[214:215] op_sel_hi:[1,0]
	v_rcp_f32_e32 v196, v196
	v_rcp_f32_e32 v197, v197
	v_rcp_f32_e32 v198, v198
	v_rcp_f32_e32 v199, v199
	v_pk_mul_f32 v[188:189], v[188:189], v[196:197]
	v_pk_mul_f32 v[190:191], v[190:191], v[198:199]
	v_pk_mul_f32 v[188:189], v[188:189], v[192:193]
	v_pk_mul_f32 v[190:191], v[190:191], v[194:195]
	v_cvt_pk_bf16_f32 v152, v188, v189
	v_cvt_pk_bf16_f32 v153, v190, v191
	v_add_u32_e32 v213, 0x58000, v215
	global_store_dwordx4 v213, v[150:153], s[96:97] nt
	v_pk_fma_f32 v[188:189], v[40:41], v[134:135], v[130:131]
	v_pk_fma_f32 v[190:191], v[42:43], v[136:137], v[132:133]
	v_pk_fma_f32 v[192:193], v[32:33], v[204:205], v[208:209]
	v_pk_fma_f32 v[194:195], v[34:35], v[206:207], v[210:211]
	v_fmac_f32_dpp v188, v40, v142 row_shr:1 row_mask:0xf bank_mask:0xf
	v_fmac_f32_dpp v189, v41, v143 row_shr:1 row_mask:0xf bank_mask:0xf
	v_fmac_f32_dpp v190, v42, v144 row_shr:1 row_mask:0xf bank_mask:0xf
	v_fmac_f32_dpp v191, v43, v145 row_shr:1 row_mask:0xf bank_mask:0xf
	v_fmac_f32_dpp v192, v32, v110 row_shr:1 row_mask:0xf bank_mask:0xf
	v_fmac_f32_dpp v193, v33, v111 row_shr:1 row_mask:0xf bank_mask:0xf
	v_fmac_f32_dpp v194, v34, v112 row_shr:1 row_mask:0xf bank_mask:0xf
	v_fmac_f32_dpp v195, v35, v113 row_shr:1 row_mask:0xf bank_mask:0xf
	v_fmac_f32_dpp v188, v40, v154 row_shr:2 row_mask:0xf bank_mask:0xf
	v_fmac_f32_dpp v189, v41, v155 row_shr:2 row_mask:0xf bank_mask:0xf
	v_fmac_f32_dpp v190, v42, v156 row_shr:2 row_mask:0xf bank_mask:0xf
	v_fmac_f32_dpp v191, v43, v157 row_shr:2 row_mask:0xf bank_mask:0xf
	v_fmac_f32_dpp v192, v32, v118 row_shr:2 row_mask:0xf bank_mask:0xf
	v_fmac_f32_dpp v193, v33, v119 row_shr:2 row_mask:0xf bank_mask:0xf
	v_fmac_f32_dpp v194, v34, v120 row_shr:2 row_mask:0xf bank_mask:0xf
	v_fmac_f32_dpp v195, v35, v121 row_shr:2 row_mask:0xf bank_mask:0xf
	v_fmac_f32_dpp v188, v48, v142 row_shl:15 row_mask:0xf bank_mask:0xf
	v_fmac_f32_dpp v189, v49, v143 row_shl:15 row_mask:0xf bank_mask:0xf
	v_fmac_f32_dpp v190, v50, v144 row_shl:15 row_mask:0xf bank_mask:0xf
	v_fmac_f32_dpp v191, v51, v145 row_shl:15 row_mask:0xf bank_mask:0xf
	v_fmac_f32_dpp v192, v36, v110 row_shl:15 row_mask:0xf bank_mask:0xf
	v_fmac_f32_dpp v193, v37, v111 row_shl:15 row_mask:0xf bank_mask:0xf
	v_fmac_f32_dpp v194, v38, v112 row_shl:15 row_mask:0xf bank_mask:0xf
	v_fmac_f32_dpp v195, v39, v113 row_shl:15 row_mask:0xf bank_mask:0xf
	v_fmac_f32_dpp v188, v48, v154 row_shl:14 row_mask:0xf bank_mask:0xf
	v_fmac_f32_dpp v189, v49, v155 row_shl:14 row_mask:0xf bank_mask:0xf
	v_fmac_f32_dpp v190, v50, v156 row_shl:14 row_mask:0xf bank_mask:0xf
	v_fmac_f32_dpp v191, v51, v157 row_shl:14 row_mask:0xf bank_mask:0xf
	v_fmac_f32_dpp v192, v36, v118 row_shl:14 row_mask:0xf bank_mask:0xf
	v_fmac_f32_dpp v193, v37, v119 row_shl:14 row_mask:0xf bank_mask:0xf
	v_fmac_f32_dpp v194, v38, v120 row_shl:14 row_mask:0xf bank_mask:0xf
	v_fmac_f32_dpp v195, v39, v121 row_shl:14 row_mask:0xf bank_mask:0xf
	v_pk_mul_f32 v[196:197], v[188:189], v[216:217] op_sel_hi:[1,0]
	v_pk_mul_f32 v[198:199], v[190:191], v[216:217] op_sel_hi:[1,0]
	v_exp_f32_e32 v196, v196
	v_exp_f32_e32 v197, v197
	v_exp_f32_e32 v198, v198
	v_exp_f32_e32 v199, v199
	v_pk_add_f32 v[196:197], v[196:197], v[214:215] op_sel_hi:[1,0]
	v_pk_add_f32 v[198:199], v[198:199], v[214:215] op_sel_hi:[1,0]
	v_rcp_f32_e32 v196, v196
	v_rcp_f32_e32 v197, v197
	v_rcp_f32_e32 v198, v198
	v_rcp_f32_e32 v199, v199
	v_pk_mul_f32 v[188:189], v[188:189], v[196:197]
	v_pk_mul_f32 v[190:191], v[190:191], v[198:199]
	v_pk_mul_f32 v[188:189], v[188:189], v[192:193]
	v_pk_mul_f32 v[190:191], v[190:191], v[194:195]
	v_cvt_pk_bf16_f32 v148, v188, v189
	v_cvt_pk_bf16_f32 v149, v190, v191
	v_add_u32_e32 v213, 0x84000, v215
	global_store_dwordx4 v213, v[146:149], s[96:97] nt
	v_pk_fma_f32 v[188:189], v[28:29], v[134:135], v[130:131]
	v_pk_fma_f32 v[190:191], v[30:31], v[136:137], v[132:133]
	v_pk_fma_f32 v[192:193], v[16:17], v[204:205], v[208:209]
	v_pk_fma_f32 v[194:195], v[18:19], v[206:207], v[210:211]
	v_fmac_f32_dpp v188, v28, v142 row_shr:1 row_mask:0xf bank_mask:0xf
	v_fmac_f32_dpp v189, v29, v143 row_shr:1 row_mask:0xf bank_mask:0xf
	v_fmac_f32_dpp v190, v30, v144 row_shr:1 row_mask:0xf bank_mask:0xf
	v_fmac_f32_dpp v191, v31, v145 row_shr:1 row_mask:0xf bank_mask:0xf
	v_fmac_f32_dpp v192, v16, v110 row_shr:1 row_mask:0xf bank_mask:0xf
	v_fmac_f32_dpp v193, v17, v111 row_shr:1 row_mask:0xf bank_mask:0xf
	v_fmac_f32_dpp v194, v18, v112 row_shr:1 row_mask:0xf bank_mask:0xf
	v_fmac_f32_dpp v195, v19, v113 row_shr:1 row_mask:0xf bank_mask:0xf
	v_fmac_f32_dpp v188, v28, v154 row_shr:2 row_mask:0xf bank_mask:0xf
	v_fmac_f32_dpp v189, v29, v155 row_shr:2 row_mask:0xf bank_mask:0xf
	v_fmac_f32_dpp v190, v30, v156 row_shr:2 row_mask:0xf bank_mask:0xf
	v_fmac_f32_dpp v191, v31, v157 row_shr:2 row_mask:0xf bank_mask:0xf
	v_fmac_f32_dpp v192, v16, v118 row_shr:2 row_mask:0xf bank_mask:0xf
	v_fmac_f32_dpp v193, v17, v119 row_shr:2 row_mask:0xf bank_mask:0xf
	v_fmac_f32_dpp v194, v18, v120 row_shr:2 row_mask:0xf bank_mask:0xf
	v_fmac_f32_dpp v195, v19, v121 row_shr:2 row_mask:0xf bank_mask:0xf
	v_fmac_f32_dpp v188, v40, v142 row_shl:15 row_mask:0xf bank_mask:0xf
	v_fmac_f32_dpp v189, v41, v143 row_shl:15 row_mask:0xf bank_mask:0xf
	v_fmac_f32_dpp v190, v42, v144 row_shl:15 row_mask:0xf bank_mask:0xf
	v_fmac_f32_dpp v191, v43, v145 row_shl:15 row_mask:0xf bank_mask:0xf
	v_fmac_f32_dpp v192, v32, v110 row_shl:15 row_mask:0xf bank_mask:0xf
	v_fmac_f32_dpp v193, v33, v111 row_shl:15 row_mask:0xf bank_mask:0xf
	v_fmac_f32_dpp v194, v34, v112 row_shl:15 row_mask:0xf bank_mask:0xf
	v_fmac_f32_dpp v195, v35, v113 row_shl:15 row_mask:0xf bank_mask:0xf
	v_fmac_f32_dpp v188, v40, v154 row_shl:14 row_mask:0xf bank_mask:0xf
	v_fmac_f32_dpp v189, v41, v155 row_shl:14 row_mask:0xf bank_mask:0xf
	v_fmac_f32_dpp v190, v42, v156 row_shl:14 row_mask:0xf bank_mask:0xf
	v_fmac_f32_dpp v191, v43, v157 row_shl:14 row_mask:0xf bank_mask:0xf
	v_fmac_f32_dpp v192, v32, v118 row_shl:14 row_mask:0xf bank_mask:0xf
	v_fmac_f32_dpp v193, v33, v119 row_shl:14 row_mask:0xf bank_mask:0xf
	v_fmac_f32_dpp v194, v34, v120 row_shl:14 row_mask:0xf bank_mask:0xf
	v_fmac_f32_dpp v195, v35, v121 row_shl:14 row_mask:0xf bank_mask:0xf
	v_pk_mul_f32 v[196:197], v[188:189], v[216:217] op_sel_hi:[1,0]
	v_pk_mul_f32 v[198:199], v[190:191], v[216:217] op_sel_hi:[1,0]
	v_exp_f32_e32 v196, v196
	v_exp_f32_e32 v197, v197
	v_exp_f32_e32 v198, v198
	v_exp_f32_e32 v199, v199
	v_pk_add_f32 v[196:197], v[196:197], v[214:215] op_sel_hi:[1,0]
	v_pk_add_f32 v[198:199], v[198:199], v[214:215] op_sel_hi:[1,0]
	v_rcp_f32_e32 v196, v196
	v_rcp_f32_e32 v197, v197
	v_rcp_f32_e32 v198, v198
	v_rcp_f32_e32 v199, v199
	v_pk_mul_f32 v[188:189], v[188:189], v[196:197]
	v_pk_mul_f32 v[190:191], v[190:191], v[198:199]
	v_pk_mul_f32 v[188:189], v[188:189], v[192:193]
	v_pk_mul_f32 v[190:191], v[190:191], v[194:195]
	v_cvt_pk_bf16_f32 v140, v188, v189
	v_cvt_pk_bf16_f32 v141, v190, v191
	v_add_u32_e32 v213, 0xb0000, v215
	global_store_dwordx4 v213, v[138:141], s[96:97] nt
	v_pk_fma_f32 v[188:189], v[24:25], v[134:135], v[130:131]
	v_pk_fma_f32 v[190:191], v[26:27], v[136:137], v[132:133]
	v_pk_fma_f32 v[192:193], v[12:13], v[204:205], v[208:209]
	v_pk_fma_f32 v[194:195], v[14:15], v[206:207], v[210:211]
	v_fmac_f32_dpp v188, v24, v142 row_shr:1 row_mask:0xf bank_mask:0xf
	v_fmac_f32_dpp v189, v25, v143 row_shr:1 row_mask:0xf bank_mask:0xf
	v_fmac_f32_dpp v190, v26, v144 row_shr:1 row_mask:0xf bank_mask:0xf
	v_fmac_f32_dpp v191, v27, v145 row_shr:1 row_mask:0xf bank_mask:0xf
	v_fmac_f32_dpp v192, v12, v110 row_shr:1 row_mask:0xf bank_mask:0xf
	v_fmac_f32_dpp v193, v13, v111 row_shr:1 row_mask:0xf bank_mask:0xf
	v_fmac_f32_dpp v194, v14, v112 row_shr:1 row_mask:0xf bank_mask:0xf
	v_fmac_f32_dpp v195, v15, v113 row_shr:1 row_mask:0xf bank_mask:0xf
	v_fmac_f32_dpp v188, v24, v154 row_shr:2 row_mask:0xf bank_mask:0xf
	v_fmac_f32_dpp v189, v25, v155 row_shr:2 row_mask:0xf bank_mask:0xf
	v_fmac_f32_dpp v190, v26, v156 row_shr:2 row_mask:0xf bank_mask:0xf
	v_fmac_f32_dpp v191, v27, v157 row_shr:2 row_mask:0xf bank_mask:0xf
	v_fmac_f32_dpp v192, v12, v118 row_shr:2 row_mask:0xf bank_mask:0xf
	v_fmac_f32_dpp v193, v13, v119 row_shr:2 row_mask:0xf bank_mask:0xf
	v_fmac_f32_dpp v194, v14, v120 row_shr:2 row_mask:0xf bank_mask:0xf
	v_fmac_f32_dpp v195, v15, v121 row_shr:2 row_mask:0xf bank_mask:0xf
	v_fmac_f32_dpp v188, v28, v142 row_shl:15 row_mask:0xf bank_mask:0xf
	v_fmac_f32_dpp v189, v29, v143 row_shl:15 row_mask:0xf bank_mask:0xf
	v_fmac_f32_dpp v190, v30, v144 row_shl:15 row_mask:0xf bank_mask:0xf
	v_fmac_f32_dpp v191, v31, v145 row_shl:15 row_mask:0xf bank_mask:0xf
	v_fmac_f32_dpp v192, v16, v110 row_shl:15 row_mask:0xf bank_mask:0xf
	v_fmac_f32_dpp v193, v17, v111 row_shl:15 row_mask:0xf bank_mask:0xf
	v_fmac_f32_dpp v194, v18, v112 row_shl:15 row_mask:0xf bank_mask:0xf
	v_fmac_f32_dpp v195, v19, v113 row_shl:15 row_mask:0xf bank_mask:0xf
	v_fmac_f32_dpp v188, v28, v154 row_shl:14 row_mask:0xf bank_mask:0xf
	v_fmac_f32_dpp v189, v29, v155 row_shl:14 row_mask:0xf bank_mask:0xf
	v_fmac_f32_dpp v190, v30, v156 row_shl:14 row_mask:0xf bank_mask:0xf
	v_fmac_f32_dpp v191, v31, v157 row_shl:14 row_mask:0xf bank_mask:0xf
	v_fmac_f32_dpp v192, v16, v118 row_shl:14 row_mask:0xf bank_mask:0xf
	v_fmac_f32_dpp v193, v17, v119 row_shl:14 row_mask:0xf bank_mask:0xf
	v_fmac_f32_dpp v194, v18, v120 row_shl:14 row_mask:0xf bank_mask:0xf
	v_fmac_f32_dpp v195, v19, v121 row_shl:14 row_mask:0xf bank_mask:0xf
	v_pk_mul_f32 v[196:197], v[188:189], v[216:217] op_sel_hi:[1,0]
	v_pk_mul_f32 v[198:199], v[190:191], v[216:217] op_sel_hi:[1,0]
	v_exp_f32_e32 v196, v196
	v_exp_f32_e32 v197, v197
	v_exp_f32_e32 v198, v198
	v_exp_f32_e32 v199, v199
	v_pk_add_f32 v[196:197], v[196:197], v[214:215] op_sel_hi:[1,0]
	v_pk_add_f32 v[198:199], v[198:199], v[214:215] op_sel_hi:[1,0]
	v_rcp_f32_e32 v196, v196
	v_rcp_f32_e32 v197, v197
	v_rcp_f32_e32 v198, v198
	v_rcp_f32_e32 v199, v199
	v_pk_mul_f32 v[188:189], v[188:189], v[196:197]
	v_pk_mul_f32 v[190:191], v[190:191], v[198:199]
	v_pk_mul_f32 v[188:189], v[188:189], v[192:193]
	v_pk_mul_f32 v[190:191], v[190:191], v[194:195]
	v_cvt_pk_bf16_f32 v128, v188, v189
	v_cvt_pk_bf16_f32 v129, v190, v191
	v_add_u32_e32 v213, 0xdc000, v215
	global_store_dwordx4 v213, v[126:129], s[96:97] nt
	v_pk_fma_f32 v[188:189], v[20:21], v[134:135], v[130:131]
	v_pk_fma_f32 v[190:191], v[22:23], v[136:137], v[132:133]
	v_pk_fma_f32 v[192:193], v[8:9], v[204:205], v[208:209]
	v_pk_fma_f32 v[194:195], v[10:11], v[206:207], v[210:211]
	v_fmac_f32_dpp v188, v20, v142 row_shr:1 row_mask:0xf bank_mask:0xf
	v_fmac_f32_dpp v189, v21, v143 row_shr:1 row_mask:0xf bank_mask:0xf
	v_fmac_f32_dpp v190, v22, v144 row_shr:1 row_mask:0xf bank_mask:0xf
	v_fmac_f32_dpp v191, v23, v145 row_shr:1 row_mask:0xf bank_mask:0xf
	v_fmac_f32_dpp v192, v8, v110 row_shr:1 row_mask:0xf bank_mask:0xf
	v_fmac_f32_dpp v193, v9, v111 row_shr:1 row_mask:0xf bank_mask:0xf
	v_fmac_f32_dpp v194, v10, v112 row_shr:1 row_mask:0xf bank_mask:0xf
	v_fmac_f32_dpp v195, v11, v113 row_shr:1 row_mask:0xf bank_mask:0xf
	v_fmac_f32_dpp v188, v20, v154 row_shr:2 row_mask:0xf bank_mask:0xf
	v_fmac_f32_dpp v189, v21, v155 row_shr:2 row_mask:0xf bank_mask:0xf
	v_fmac_f32_dpp v190, v22, v156 row_shr:2 row_mask:0xf bank_mask:0xf
	v_fmac_f32_dpp v191, v23, v157 row_shr:2 row_mask:0xf bank_mask:0xf
	v_fmac_f32_dpp v192, v8, v118 row_shr:2 row_mask:0xf bank_mask:0xf
	v_fmac_f32_dpp v193, v9, v119 row_shr:2 row_mask:0xf bank_mask:0xf
	v_fmac_f32_dpp v194, v10, v120 row_shr:2 row_mask:0xf bank_mask:0xf
	v_fmac_f32_dpp v195, v11, v121 row_shr:2 row_mask:0xf bank_mask:0xf
	v_fmac_f32_dpp v188, v24, v142 row_shl:15 row_mask:0xf bank_mask:0xf
	v_fmac_f32_dpp v189, v25, v143 row_shl:15 row_mask:0xf bank_mask:0xf
	v_fmac_f32_dpp v190, v26, v144 row_shl:15 row_mask:0xf bank_mask:0xf
	v_fmac_f32_dpp v191, v27, v145 row_shl:15 row_mask:0xf bank_mask:0xf
	v_fmac_f32_dpp v192, v12, v110 row_shl:15 row_mask:0xf bank_mask:0xf
	v_fmac_f32_dpp v193, v13, v111 row_shl:15 row_mask:0xf bank_mask:0xf
	v_fmac_f32_dpp v194, v14, v112 row_shl:15 row_mask:0xf bank_mask:0xf
	v_fmac_f32_dpp v195, v15, v113 row_shl:15 row_mask:0xf bank_mask:0xf
	v_fmac_f32_dpp v188, v24, v154 row_shl:14 row_mask:0xf bank_mask:0xf
	v_fmac_f32_dpp v189, v25, v155 row_shl:14 row_mask:0xf bank_mask:0xf
	v_fmac_f32_dpp v190, v26, v156 row_shl:14 row_mask:0xf bank_mask:0xf
	v_fmac_f32_dpp v191, v27, v157 row_shl:14 row_mask:0xf bank_mask:0xf
	v_fmac_f32_dpp v192, v12, v118 row_shl:14 row_mask:0xf bank_mask:0xf
	v_fmac_f32_dpp v193, v13, v119 row_shl:14 row_mask:0xf bank_mask:0xf
	v_fmac_f32_dpp v194, v14, v120 row_shl:14 row_mask:0xf bank_mask:0xf
	v_fmac_f32_dpp v195, v15, v121 row_shl:14 row_mask:0xf bank_mask:0xf
	v_pk_mul_f32 v[196:197], v[188:189], v[216:217] op_sel_hi:[1,0]
	v_pk_mul_f32 v[198:199], v[190:191], v[216:217] op_sel_hi:[1,0]
	v_exp_f32_e32 v196, v196
	v_exp_f32_e32 v197, v197
	v_exp_f32_e32 v198, v198
	v_exp_f32_e32 v199, v199
	v_pk_add_f32 v[196:197], v[196:197], v[214:215] op_sel_hi:[1,0]
	v_pk_add_f32 v[198:199], v[198:199], v[214:215] op_sel_hi:[1,0]
	v_rcp_f32_e32 v196, v196
	v_rcp_f32_e32 v197, v197
	v_rcp_f32_e32 v198, v198
	v_rcp_f32_e32 v199, v199
	v_pk_mul_f32 v[188:189], v[188:189], v[196:197]
	v_pk_mul_f32 v[190:191], v[190:191], v[198:199]
	v_pk_mul_f32 v[188:189], v[188:189], v[192:193]
	v_pk_mul_f32 v[190:191], v[190:191], v[194:195]
	v_cvt_pk_bf16_f32 v124, v188, v189
	v_cvt_pk_bf16_f32 v125, v190, v191
	v_add_u32_e32 v213, 0x108000, v215
	global_store_dwordx4 v213, v[122:125], s[96:97] nt
	v_pk_fma_f32 v[188:189], v[4:5], v[134:135], v[130:131]
	v_pk_fma_f32 v[190:191], v[6:7], v[136:137], v[132:133]
	v_pk_fma_f32 v[192:193], v[0:1], v[204:205], v[208:209]
	v_pk_fma_f32 v[194:195], v[2:3], v[206:207], v[210:211]
	v_fmac_f32_dpp v188, v4, v142 row_shr:1 row_mask:0xf bank_mask:0xf
	v_fmac_f32_dpp v189, v5, v143 row_shr:1 row_mask:0xf bank_mask:0xf
	v_fmac_f32_dpp v190, v6, v144 row_shr:1 row_mask:0xf bank_mask:0xf
	v_fmac_f32_dpp v191, v7, v145 row_shr:1 row_mask:0xf bank_mask:0xf
	v_fmac_f32_dpp v192, v0, v110 row_shr:1 row_mask:0xf bank_mask:0xf
	v_fmac_f32_dpp v193, v1, v111 row_shr:1 row_mask:0xf bank_mask:0xf
	v_fmac_f32_dpp v194, v2, v112 row_shr:1 row_mask:0xf bank_mask:0xf
	v_fmac_f32_dpp v195, v3, v113 row_shr:1 row_mask:0xf bank_mask:0xf
	v_fmac_f32_dpp v188, v4, v154 row_shr:2 row_mask:0xf bank_mask:0xf
	v_fmac_f32_dpp v189, v5, v155 row_shr:2 row_mask:0xf bank_mask:0xf
	v_fmac_f32_dpp v190, v6, v156 row_shr:2 row_mask:0xf bank_mask:0xf
	v_fmac_f32_dpp v191, v7, v157 row_shr:2 row_mask:0xf bank_mask:0xf
	v_fmac_f32_dpp v192, v0, v118 row_shr:2 row_mask:0xf bank_mask:0xf
	v_fmac_f32_dpp v193, v1, v119 row_shr:2 row_mask:0xf bank_mask:0xf
	v_fmac_f32_dpp v194, v2, v120 row_shr:2 row_mask:0xf bank_mask:0xf
	v_fmac_f32_dpp v195, v3, v121 row_shr:2 row_mask:0xf bank_mask:0xf
	v_fmac_f32_dpp v188, v20, v142 row_shl:15 row_mask:0xf bank_mask:0xf
	v_fmac_f32_dpp v189, v21, v143 row_shl:15 row_mask:0xf bank_mask:0xf
	v_fmac_f32_dpp v190, v22, v144 row_shl:15 row_mask:0xf bank_mask:0xf
	v_fmac_f32_dpp v191, v23, v145 row_shl:15 row_mask:0xf bank_mask:0xf
	v_fmac_f32_dpp v192, v8, v110 row_shl:15 row_mask:0xf bank_mask:0xf
	v_fmac_f32_dpp v193, v9, v111 row_shl:15 row_mask:0xf bank_mask:0xf
	v_fmac_f32_dpp v194, v10, v112 row_shl:15 row_mask:0xf bank_mask:0xf
	v_fmac_f32_dpp v195, v11, v113 row_shl:15 row_mask:0xf bank_mask:0xf
	v_fmac_f32_dpp v188, v20, v154 row_shl:14 row_mask:0xf bank_mask:0xf
	v_fmac_f32_dpp v189, v21, v155 row_shl:14 row_mask:0xf bank_mask:0xf
	v_fmac_f32_dpp v190, v22, v156 row_shl:14 row_mask:0xf bank_mask:0xf
	v_fmac_f32_dpp v191, v23, v157 row_shl:14 row_mask:0xf bank_mask:0xf
	v_fmac_f32_dpp v192, v8, v118 row_shl:14 row_mask:0xf bank_mask:0xf
	v_fmac_f32_dpp v193, v9, v119 row_shl:14 row_mask:0xf bank_mask:0xf
	v_fmac_f32_dpp v194, v10, v120 row_shl:14 row_mask:0xf bank_mask:0xf
	v_fmac_f32_dpp v195, v11, v121 row_shl:14 row_mask:0xf bank_mask:0xf
	v_pk_mul_f32 v[196:197], v[188:189], v[216:217] op_sel_hi:[1,0]
	v_pk_mul_f32 v[198:199], v[190:191], v[216:217] op_sel_hi:[1,0]
	v_exp_f32_e32 v196, v196
	v_exp_f32_e32 v197, v197
	v_exp_f32_e32 v198, v198
	v_exp_f32_e32 v199, v199
	v_pk_add_f32 v[196:197], v[196:197], v[214:215] op_sel_hi:[1,0]
	v_pk_add_f32 v[198:199], v[198:199], v[214:215] op_sel_hi:[1,0]
	v_rcp_f32_e32 v196, v196
	v_rcp_f32_e32 v197, v197
	v_rcp_f32_e32 v198, v198
	v_rcp_f32_e32 v199, v199
	v_pk_mul_f32 v[188:189], v[188:189], v[196:197]
	v_pk_mul_f32 v[190:191], v[190:191], v[198:199]
	v_pk_mul_f32 v[188:189], v[188:189], v[192:193]
	v_pk_mul_f32 v[190:191], v[190:191], v[194:195]
	v_cvt_pk_bf16_f32 v116, v188, v189
	v_cvt_pk_bf16_f32 v117, v190, v191
	v_add_u32_e32 v213, 0x134000, v215
	global_store_dwordx4 v213, v[114:117], s[96:97] nt
	s_branch .LBB0_359

.Lst_out_s8:
	s_lshl_b32 s8, s0, 8
	s_add_i32 s8, s8, s58
	s_lshl_b32 s9, s1, 7
	s_add_i32 s9, s9, s53
	s_lshl_b32 s10, s0, 3
	s_lshr_b32 s11, s58, 5
	s_add_i32 s10, s10, s11
	v_add_u32_e32 v200, s8, v163
	v_lshlrev_b32_e32 v213, 2, v200
	global_load_dword v188, v213, s[4:5]
	global_load_dword v189, v213, s[4:5] offset:64
	global_load_dword v190, v213, s[4:5] offset:128
	global_load_dword v191, v213, s[4:5] offset:192
	global_load_dword v192, v213, s[4:5] offset:256
	global_load_dword v193, v213, s[4:5] offset:320
	global_load_dword v194, v213, s[4:5] offset:384
	global_load_dword v195, v213, s[4:5] offset:448
	v_lshl_add_u32 v201, v225, 3, s9
	v_lshlrev_b32_e32 v212, 2, v201
	v_add_u32_e32 v213, 0x21000, v212
	global_load_dwordx4 v[76:79], v213, s[82:83]
	v_add_u32_e32 v213, 0x2c000, v212
	global_load_dwordx4 v[80:83], v213, s[82:83]
	v_add_u32_e32 v213, 0x37000, v212
	global_load_dwordx4 v[84:87], v213, s[82:83]
	v_add_u32_e32 v213, 0xb000, v212
	global_load_dwordx4 v[88:91], v213, s[84:85]
	v_add_u32_e32 v213, 0x26800, v212
	global_load_dwordx4 v[92:95], v213, s[82:83]
	v_add_u32_e32 v213, 0x31800, v212
	global_load_dwordx4 v[96:99], v213, s[82:83]
	v_add_u32_e32 v213, 0x3c800, v212
	global_load_dwordx4 v[100:103], v213, s[82:83]
	v_add_u32_e32 v213, 0x10800, v212
	global_load_dwordx4 v[104:107], v213, s[84:85]
	v_mul_u32_u24_e32 v215, 0x2c00, v200
	v_lshl_add_u32 v215, v201, 1, v215
	v_add_u32_e32 v213, s10, v163
	v_mul_u32_u24_e32 v217, 0xb000, v213
	v_add_u32_e32 v217, v217, v212
	v_cmp_gt_u32_e64 s[8:9], 2, v163
	v_cmp_lt_u32_e64 s[10:11], 13, v163
	v_cmp_lt_u32_e32 vcc, 1, v163
	v_mov_b32_e32 v214, 1.0
	v_mov_b32_e32 v216, 0xbfb8aa3b
	v_mov_b32_e32 v108, 0x3727c5ac
	s_waitcnt vmcnt(8)
	v_fmamk_f32 v188, v188, 0x3a000000, v108
	v_fmamk_f32 v189, v189, 0x3a000000, v108
	v_fmamk_f32 v190, v190, 0x3a000000, v108
	v_fmamk_f32 v191, v191, 0x3a000000, v108
	v_fmamk_f32 v192, v192, 0x3a000000, v108
	v_fmamk_f32 v193, v193, 0x3a000000, v108
	v_fmamk_f32 v194, v194, 0x3a000000, v108
	v_fmamk_f32 v195, v195, 0x3a000000, v108
	v_rsq_f32_e32 v188, v188
	v_rsq_f32_e32 v189, v189
	v_rsq_f32_e32 v190, v190
	v_rsq_f32_e32 v191, v191
	v_rsq_f32_e32 v192, v192
	v_rsq_f32_e32 v193, v193
	v_rsq_f32_e32 v194, v194
	v_rsq_f32_e32 v195, v195
	v_pk_mul_f32 v[158:159], v[158:159], v[188:189] op_sel_hi:[1,0]
	v_pk_mul_f32 v[160:161], v[160:161], v[188:189] op_sel_hi:[1,0]
	v_pk_mul_f32 v[60:61], v[60:61], v[188:189] op_sel_hi:[1,0]
	v_pk_mul_f32 v[62:63], v[62:63], v[188:189] op_sel_hi:[1,0]
	v_pk_mul_f32 v[154:155], v[154:155], v[188:189] op_sel_hi:[1,0]
	v_pk_mul_f32 v[156:157], v[156:157], v[188:189] op_sel_hi:[1,0]
	v_pk_mul_f32 v[56:57], v[56:57], v[188:189] op_sel_hi:[1,0]
	v_pk_mul_f32 v[58:59], v[58:59], v[188:189] op_sel_hi:[1,0]
	v_pk_mul_f32 v[150:151], v[150:151], v[188:189] op_sel:[0,1] op_sel_hi:[1,1]
	v_pk_mul_f32 v[152:153], v[152:153], v[188:189] op_sel:[0,1] op_sel_hi:[1,1]
	v_pk_mul_f32 v[52:53], v[52:53], v[188:189] op_sel:[0,1] op_sel_hi:[1,1]
	v_pk_mul_f32 v[54:55], v[54:55], v[188:189] op_sel:[0,1] op_sel_hi:[1,1]
	v_pk_mul_f32 v[142:143], v[142:143], v[188:189] op_sel:[0,1] op_sel_hi:[1,1]
	v_pk_mul_f32 v[144:145], v[144:145], v[188:189] op_sel:[0,1] op_sel_hi:[1,1]
	v_pk_mul_f32 v[44:45], v[44:45], v[188:189] op_sel:[0,1] op_sel_hi:[1,1]
	v_pk_mul_f32 v[46:47], v[46:47], v[188:189] op_sel:[0,1] op_sel_hi:[1,1]
	v_pk_mul_f32 v[146:147], v[146:147], v[190:191] op_sel_hi:[1,0]
	v_pk_mul_f32 v[148:149], v[148:149], v[190:191] op_sel_hi:[1,0]
	v_pk_mul_f32 v[48:49], v[48:49], v[190:191] op_sel_hi:[1,0]
	v_pk_mul_f32 v[50:51], v[50:51], v[190:191] op_sel_hi:[1,0]
	v_pk_mul_f32 v[134:135], v[134:135], v[190:191] op_sel_hi:[1,0]
	v_pk_mul_f32 v[136:137], v[136:137], v[190:191] op_sel_hi:[1,0]
	v_pk_mul_f32 v[36:37], v[36:37], v[190:191] op_sel_hi:[1,0]
	v_pk_mul_f32 v[38:39], v[38:39], v[190:191] op_sel_hi:[1,0]
	v_pk_mul_f32 v[138:139], v[138:139], v[190:191] op_sel:[0,1] op_sel_hi:[1,1]
	v_pk_mul_f32 v[140:141], v[140:141], v[190:191] op_sel:[0,1] op_sel_hi:[1,1]
	v_pk_mul_f32 v[40:41], v[40:41], v[190:191] op_sel:[0,1] op_sel_hi:[1,1]
	v_pk_mul_f32 v[42:43], v[42:43], v[190:191] op_sel:[0,1] op_sel_hi:[1,1]
	v_pk_mul_f32 v[130:131], v[130:131], v[190:191] op_sel:[0,1] op_sel_hi:[1,1]
	v_pk_mul_f32 v[132:133], v[132:133], v[190:191] op_sel:[0,1] op_sel_hi:[1,1]
	v_pk_mul_f32 v[32:33], v[32:33], v[190:191] op_sel:[0,1] op_sel_hi:[1,1]
	v_pk_mul_f32 v[34:35], v[34:35], v[190:191] op_sel:[0,1] op_sel_hi:[1,1]
	v_pk_mul_f32 v[126:127], v[126:127], v[192:193] op_sel_hi:[1,0]
	v_pk_mul_f32 v[128:129], v[128:129], v[192:193] op_sel_hi:[1,0]
	v_pk_mul_f32 v[28:29], v[28:29], v[192:193] op_sel_hi:[1,0]
	v_pk_mul_f32 v[30:31], v[30:31], v[192:193] op_sel_hi:[1,0]
	v_pk_mul_f32 v[118:119], v[118:119], v[192:193] op_sel_hi:[1,0]
	v_pk_mul_f32 v[120:121], v[120:121], v[192:193] op_sel_hi:[1,0]
	v_pk_mul_f32 v[16:17], v[16:17], v[192:193] op_sel_hi:[1,0]
	v_pk_mul_f32 v[18:19], v[18:19], v[192:193] op_sel_hi:[1,0]
	v_pk_mul_f32 v[122:123], v[122:123], v[192:193] op_sel:[0,1] op_sel_hi:[1,1]
	v_pk_mul_f32 v[124:125], v[124:125], v[192:193] op_sel:[0,1] op_sel_hi:[1,1]
	v_pk_mul_f32 v[24:25], v[24:25], v[192:193] op_sel:[0,1] op_sel_hi:[1,1]
	v_pk_mul_f32 v[26:27], v[26:27], v[192:193] op_sel:[0,1] op_sel_hi:[1,1]
	v_pk_mul_f32 v[110:111], v[110:111], v[192:193] op_sel:[0,1] op_sel_hi:[1,1]
	v_pk_mul_f32 v[112:113], v[112:113], v[192:193] op_sel:[0,1] op_sel_hi:[1,1]
	v_pk_mul_f32 v[12:13], v[12:13], v[192:193] op_sel:[0,1] op_sel_hi:[1,1]
	v_pk_mul_f32 v[14:15], v[14:15], v[192:193] op_sel:[0,1] op_sel_hi:[1,1]
	v_pk_mul_f32 v[114:115], v[114:115], v[194:195] op_sel_hi:[1,0]
	v_pk_mul_f32 v[116:117], v[116:117], v[194:195] op_sel_hi:[1,0]
	v_pk_mul_f32 v[20:21], v[20:21], v[194:195] op_sel_hi:[1,0]
	v_pk_mul_f32 v[22:23], v[22:23], v[194:195] op_sel_hi:[1,0]
	v_pk_mul_f32 v[68:69], v[68:69], v[194:195] op_sel_hi:[1,0]
	v_pk_mul_f32 v[70:71], v[70:71], v[194:195] op_sel_hi:[1,0]
	v_pk_mul_f32 v[8:9], v[8:9], v[194:195] op_sel_hi:[1,0]
	v_pk_mul_f32 v[10:11], v[10:11], v[194:195] op_sel_hi:[1,0]
	v_pk_mul_f32 v[72:73], v[72:73], v[194:195] op_sel:[0,1] op_sel_hi:[1,1]
	v_pk_mul_f32 v[74:75], v[74:75], v[194:195] op_sel:[0,1] op_sel_hi:[1,1]
	v_pk_mul_f32 v[4:5], v[4:5], v[194:195] op_sel:[0,1] op_sel_hi:[1,1]
	v_pk_mul_f32 v[6:7], v[6:7], v[194:195] op_sel:[0,1] op_sel_hi:[1,1]
	v_pk_mul_f32 v[64:65], v[64:65], v[194:195] op_sel:[0,1] op_sel_hi:[1,1]
	v_pk_mul_f32 v[66:67], v[66:67], v[194:195] op_sel:[0,1] op_sel_hi:[1,1]
	v_pk_mul_f32 v[0:1], v[0:1], v[194:195] op_sel:[0,1] op_sel_hi:[1,1]
	v_pk_mul_f32 v[2:3], v[2:3], v[194:195] op_sel:[0,1] op_sel_hi:[1,1]
	s_nop 1
	s_mov_b64 exec, s[8:9]
	v_add_u32_e32 v213, 0x5800, v217
	global_store_dwordx4 v217, v[158:161], s[70:71]
	global_store_dwordx4 v213, v[154:157], s[70:71]
	global_store_dwordx4 v217, v[60:63], s[70:71] offset:16
	global_store_dwordx4 v213, v[56:59], s[70:71] offset:16
	s_mov_b64 exec, s[10:11]
	v_add_u32_e32 v213, 0xfff7c000, v217
	global_store_dwordx4 v213, v[72:75], s[70:71]
	global_store_dwordx4 v213, v[4:7], s[70:71] offset:16
	v_add_u32_e32 v213, 0xfff81800, v217
	global_store_dwordx4 v213, v[64:67], s[70:71]
	global_store_dwordx4 v213, v[0:3], s[70:71] offset:16
	s_mov_b64 exec, -1
	v_add_u32_e32 v213, 0x3c800, v212
	global_load_dwordx4 v[204:207], v213, s[82:83] offset:16
	v_add_u32_e32 v213, 0x10800, v212
	global_load_dwordx4 v[208:211], v213, s[84:85] offset:16
	s_waitcnt vmcnt(10)
	v_pk_fma_f32 v[188:189], v[158:159], v[84:85], v[88:89]
	v_pk_fma_f32 v[190:191], v[160:161], v[86:87], v[90:91]
	v_pk_fma_f32 v[192:193], v[154:155], v[100:101], v[104:105]
	v_pk_fma_f32 v[194:195], v[156:157], v[102:103], v[106:107]
	v_fmac_f32_dpp v188, v158, v80 row_shr:1 row_mask:0xf bank_mask:0xf
	v_fmac_f32_dpp v189, v159, v81 row_shr:1 row_mask:0xf bank_mask:0xf
	v_fmac_f32_dpp v190, v160, v82 row_shr:1 row_mask:0xf bank_mask:0xf
	v_fmac_f32_dpp v191, v161, v83 row_shr:1 row_mask:0xf bank_mask:0xf
	v_fmac_f32_dpp v192, v154, v96 row_shr:1 row_mask:0xf bank_mask:0xf
	v_fmac_f32_dpp v193, v155, v97 row_shr:1 row_mask:0xf bank_mask:0xf
	v_fmac_f32_dpp v194, v156, v98 row_shr:1 row_mask:0xf bank_mask:0xf
	v_fmac_f32_dpp v195, v157, v99 row_shr:1 row_mask:0xf bank_mask:0xf
	v_fmac_f32_dpp v188, v158, v76 row_shr:2 row_mask:0xf bank_mask:0xf
	v_fmac_f32_dpp v189, v159, v77 row_shr:2 row_mask:0xf bank_mask:0xf
	v_fmac_f32_dpp v190, v160, v78 row_shr:2 row_mask:0xf bank_mask:0xf
	v_fmac_f32_dpp v191, v161, v79 row_shr:2 row_mask:0xf bank_mask:0xf
	v_fmac_f32_dpp v192, v154, v92 row_shr:2 row_mask:0xf bank_mask:0xf
	v_fmac_f32_dpp v193, v155, v93 row_shr:2 row_mask:0xf bank_mask:0xf
	v_fmac_f32_dpp v194, v156, v94 row_shr:2 row_mask:0xf bank_mask:0xf
	v_fmac_f32_dpp v195, v157, v95 row_shr:2 row_mask:0xf bank_mask:0xf
	v_pk_mul_f32 v[196:197], v[188:189], v[216:217] op_sel_hi:[1,0]
	v_pk_mul_f32 v[198:199], v[190:191], v[216:217] op_sel_hi:[1,0]
	v_exp_f32_e32 v196, v196
	v_exp_f32_e32 v197, v197
	v_exp_f32_e32 v198, v198
	v_exp_f32_e32 v199, v199
	v_pk_add_f32 v[196:197], v[196:197], v[214:215] op_sel_hi:[1,0]
	v_pk_add_f32 v[198:199], v[198:199], v[214:215] op_sel_hi:[1,0]
	v_rcp_f32_e32 v196, v196
	v_rcp_f32_e32 v197, v197
	v_rcp_f32_e32 v198, v198
	v_rcp_f32_e32 v199, v199
	v_pk_mul_f32 v[188:189], v[188:189], v[196:197]
	v_pk_mul_f32 v[190:191], v[190:191], v[198:199]
	v_pk_mul_f32 v[188:189], v[188:189], v[192:193]
	v_pk_mul_f32 v[190:191], v[190:191], v[194:195]
	v_cvt_pk_bf16_f32 v200, v188, v189
	v_cvt_pk_bf16_f32 v201, v190, v191
	v_pk_fma_f32 v[188:189], v[150:151], v[84:85], v[88:89]
	v_pk_fma_f32 v[190:191], v[152:153], v[86:87], v[90:91]
	v_pk_fma_f32 v[192:193], v[142:143], v[100:101], v[104:105]
	v_pk_fma_f32 v[194:195], v[144:145], v[102:103], v[106:107]
	v_fmac_f32_dpp v188, v150, v80 row_shr:1 row_mask:0xf bank_mask:0xf
	v_fmac_f32_dpp v189, v151, v81 row_shr:1 row_mask:0xf bank_mask:0xf
	v_fmac_f32_dpp v190, v152, v82 row_shr:1 row_mask:0xf bank_mask:0xf
	v_fmac_f32_dpp v191, v153, v83 row_shr:1 row_mask:0xf bank_mask:0xf
	v_fmac_f32_dpp v192, v142, v96 row_shr:1 row_mask:0xf bank_mask:0xf
	v_fmac_f32_dpp v193, v143, v97 row_shr:1 row_mask:0xf bank_mask:0xf
	v_fmac_f32_dpp v194, v144, v98 row_shr:1 row_mask:0xf bank_mask:0xf
	v_fmac_f32_dpp v195, v145, v99 row_shr:1 row_mask:0xf bank_mask:0xf
	v_fmac_f32_dpp v188, v150, v76 row_shr:2 row_mask:0xf bank_mask:0xf
	v_fmac_f32_dpp v189, v151, v77 row_shr:2 row_mask:0xf bank_mask:0xf
	v_fmac_f32_dpp v190, v152, v78 row_shr:2 row_mask:0xf bank_mask:0xf
	v_fmac_f32_dpp v191, v153, v79 row_shr:2 row_mask:0xf bank_mask:0xf
	v_fmac_f32_dpp v192, v142, v92 row_shr:2 row_mask:0xf bank_mask:0xf
	v_fmac_f32_dpp v193, v143, v93 row_shr:2 row_mask:0xf bank_mask:0xf
	v_fmac_f32_dpp v194, v144, v94 row_shr:2 row_mask:0xf bank_mask:0xf
	v_fmac_f32_dpp v195, v145, v95 row_shr:2 row_mask:0xf bank_mask:0xf
	v_fmac_f32_dpp v188, v158, v80 row_shl:15 row_mask:0xf bank_mask:0xf
	v_fmac_f32_dpp v189, v159, v81 row_shl:15 row_mask:0xf bank_mask:0xf
	v_fmac_f32_dpp v190, v160, v82 row_shl:15 row_mask:0xf bank_mask:0xf
	v_fmac_f32_dpp v191, v161, v83 row_shl:15 row_mask:0xf bank_mask:0xf
	v_fmac_f32_dpp v192, v154, v96 row_shl:15 row_mask:0xf bank_mask:0xf
	v_fmac_f32_dpp v193, v155, v97 row_shl:15 row_mask:0xf bank_mask:0xf
	v_fmac_f32_dpp v194, v156, v98 row_shl:15 row_mask:0xf bank_mask:0xf
	v_fmac_f32_dpp v195, v157, v99 row_shl:15 row_mask:0xf bank_mask:0xf
	v_fmac_f32_dpp v188, v158, v76 row_shl:14 row_mask:0xf bank_mask:0xf
	v_fmac_f32_dpp v189, v159, v77 row_shl:14 row_mask:0xf bank_mask:0xf
	v_fmac_f32_dpp v190, v160, v78 row_shl:14 row_mask:0xf bank_mask:0xf
	v_fmac_f32_dpp v191, v161, v79 row_shl:14 row_mask:0xf bank_mask:0xf
	v_fmac_f32_dpp v192, v154, v92 row_shl:14 row_mask:0xf bank_mask:0xf
	v_fmac_f32_dpp v193, v155, v93 row_shl:14 row_mask:0xf bank_mask:0xf
	v_fmac_f32_dpp v194, v156, v94 row_shl:14 row_mask:0xf bank_mask:0xf
	v_fmac_f32_dpp v195, v157, v95 row_shl:14 row_mask:0xf bank_mask:0xf
	v_pk_mul_f32 v[196:197], v[188:189], v[216:217] op_sel_hi:[1,0]
	v_pk_mul_f32 v[198:199], v[190:191], v[216:217] op_sel_hi:[1,0]
	v_exp_f32_e32 v196, v196
	v_exp_f32_e32 v197, v197
	v_exp_f32_e32 v198, v198
	v_exp_f32_e32 v199, v199
	v_pk_add_f32 v[196:197], v[196:197], v[214:215] op_sel_hi:[1,0]
	v_pk_add_f32 v[198:199], v[198:199], v[214:215] op_sel_hi:[1,0]
	v_rcp_f32_e32 v196, v196
	v_rcp_f32_e32 v197, v197
	v_rcp_f32_e32 v198, v198
	v_rcp_f32_e32 v199, v199
	v_pk_mul_f32 v[188:189], v[188:189], v[196:197]
	v_pk_mul_f32 v[190:191], v[190:191], v[198:199]
	v_pk_mul_f32 v[188:189], v[188:189], v[192:193]
	v_pk_mul_f32 v[190:191], v[190:191], v[194:195]
	v_cvt_pk_bf16_f32 v158, v188, v189
	v_cvt_pk_bf16_f32 v159, v190, v191
	v_add_u32_e32 v213, 0x21000, v212
	global_load_dwordx4 v[154:157], v213, s[82:83] offset:16
	v_pk_fma_f32 v[188:189], v[146:147], v[84:85], v[88:89]
	v_pk_fma_f32 v[190:191], v[148:149], v[86:87], v[90:91]
	v_pk_fma_f32 v[192:193], v[134:135], v[100:101], v[104:105]
	v_pk_fma_f32 v[194:195], v[136:137], v[102:103], v[106:107]
	v_fmac_f32_dpp v188, v146, v80 row_shr:1 row_mask:0xf bank_mask:0xf
	v_fmac_f32_dpp v189, v147, v81 row_shr:1 row_mask:0xf bank_mask:0xf
	v_fmac_f32_dpp v190, v148, v82 row_shr:1 row_mask:0xf bank_mask:0xf
	v_fmac_f32_dpp v191, v149, v83 row_shr:1 row_mask:0xf bank_mask:0xf
	v_fmac_f32_dpp v192, v134, v96 row_shr:1 row_mask:0xf bank_mask:0xf
	v_fmac_f32_dpp v193, v135, v97 row_shr:1 row_mask:0xf bank_mask:0xf
	v_fmac_f32_dpp v194, v136, v98 row_shr:1 row_mask:0xf bank_mask:0xf
	v_fmac_f32_dpp v195, v137, v99 row_shr:1 row_mask:0xf bank_mask:0xf
	v_fmac_f32_dpp v188, v146, v76 row_shr:2 row_mask:0xf bank_mask:0xf
	v_fmac_f32_dpp v189, v147, v77 row_shr:2 row_mask:0xf bank_mask:0xf
	v_fmac_f32_dpp v190, v148, v78 row_shr:2 row_mask:0xf bank_mask:0xf
	v_fmac_f32_dpp v191, v149, v79 row_shr:2 row_mask:0xf bank_mask:0xf
	v_fmac_f32_dpp v192, v134, v92 row_shr:2 row_mask:0xf bank_mask:0xf
	v_fmac_f32_dpp v193, v135, v93 row_shr:2 row_mask:0xf bank_mask:0xf
	v_fmac_f32_dpp v194, v136, v94 row_shr:2 row_mask:0xf bank_mask:0xf
	v_fmac_f32_dpp v195, v137, v95 row_shr:2 row_mask:0xf bank_mask:0xf
	v_fmac_f32_dpp v188, v150, v80 row_shl:15 row_mask:0xf bank_mask:0xf
	v_fmac_f32_dpp v189, v151, v81 row_shl:15 row_mask:0xf bank_mask:0xf
	v_fmac_f32_dpp v190, v152, v82 row_shl:15 row_mask:0xf bank_mask:0xf
	v_fmac_f32_dpp v191, v153, v83 row_shl:15 row_mask:0xf bank_mask:0xf
	v_fmac_f32_dpp v192, v142, v96 row_shl:15 row_mask:0xf bank_mask:0xf
	v_fmac_f32_dpp v193, v143, v97 row_shl:15 row_mask:0xf bank_mask:0xf
	v_fmac_f32_dpp v194, v144, v98 row_shl:15 row_mask:0xf bank_mask:0xf
	v_fmac_f32_dpp v195, v145, v99 row_shl:15 row_mask:0xf bank_mask:0xf
	v_fmac_f32_dpp v188, v150, v76 row_shl:14 row_mask:0xf bank_mask:0xf
	v_fmac_f32_dpp v189, v151, v77 row_shl:14 row_mask:0xf bank_mask:0xf
	v_fmac_f32_dpp v190, v152, v78 row_shl:14 row_mask:0xf bank_mask:0xf
	v_fmac_f32_dpp v191, v153, v79 row_shl:14 row_mask:0xf bank_mask:0xf
	v_fmac_f32_dpp v192, v142, v92 row_shl:14 row_mask:0xf bank_mask:0xf
	v_fmac_f32_dpp v193, v143, v93 row_shl:14 row_mask:0xf bank_mask:0xf
	v_fmac_f32_dpp v194, v144, v94 row_shl:14 row_mask:0xf bank_mask:0xf
	v_fmac_f32_dpp v195, v145, v95 row_shl:14 row_mask:0xf bank_mask:0xf
	v_pk_mul_f32 v[196:197], v[188:189], v[216:217] op_sel_hi:[1,0]
	v_pk_mul_f32 v[198:199], v[190:191], v[216:217] op_sel_hi:[1,0]
	v_exp_f32_e32 v196, v196
	v_exp_f32_e32 v197, v197
	v_exp_f32_e32 v198, v198
	v_exp_f32_e32 v199, v199
	v_pk_add_f32 v[196:197], v[196:197], v[214:215] op_sel_hi:[1,0]
	v_pk_add_f32 v[198:199], v[198:199], v[214:215] op_sel_hi:[1,0]
	v_rcp_f32_e32 v196, v196
	v_rcp_f32_e32 v197, v197
	v_rcp_f32_e32 v198, v198
	v_rcp_f32_e32 v199, v199
	v_pk_mul_f32 v[188:189], v[188:189], v[196:197]
	v_pk_mul_f32 v[190:191], v[190:191], v[198:199]
	v_pk_mul_f32 v[188:189], v[188:189], v[192:193]
	v_pk_mul_f32 v[190:191], v[190:191], v[194:195]
	v_cvt_pk_bf16_f32 v150, v188, v189
	v_cvt_pk_bf16_f32 v151, v190, v191
	v_add_u32_e32 v213, 0x2c000, v212
	global_load_dwordx4 v[142:145], v213, s[82:83] offset:16
	v_pk_fma_f32 v[188:189], v[138:139], v[84:85], v[88:89]
	v_pk_fma_f32 v[190:191], v[140:141], v[86:87], v[90:91]
	v_pk_fma_f32 v[192:193], v[130:131], v[100:101], v[104:105]
	v_pk_fma_f32 v[194:195], v[132:133], v[102:103], v[106:107]
	v_fmac_f32_dpp v188, v138, v80 row_shr:1 row_mask:0xf bank_mask:0xf
	v_fmac_f32_dpp v189, v139, v81 row_shr:1 row_mask:0xf bank_mask:0xf
	v_fmac_f32_dpp v190, v140, v82 row_shr:1 row_mask:0xf bank_mask:0xf
	v_fmac_f32_dpp v191, v141, v83 row_shr:1 row_mask:0xf bank_mask:0xf
	v_fmac_f32_dpp v192, v130, v96 row_shr:1 row_mask:0xf bank_mask:0xf
	v_fmac_f32_dpp v193, v131, v97 row_shr:1 row_mask:0xf bank_mask:0xf
	v_fmac_f32_dpp v194, v132, v98 row_shr:1 row_mask:0xf bank_mask:0xf
	v_fmac_f32_dpp v195, v133, v99 row_shr:1 row_mask:0xf bank_mask:0xf
	v_fmac_f32_dpp v188, v138, v76 row_shr:2 row_mask:0xf bank_mask:0xf
	v_fmac_f32_dpp v189, v139, v77 row_shr:2 row_mask:0xf bank_mask:0xf
	v_fmac_f32_dpp v190, v140, v78 row_shr:2 row_mask:0xf bank_mask:0xf
	v_fmac_f32_dpp v191, v141, v79 row_shr:2 row_mask:0xf bank_mask:0xf
	v_fmac_f32_dpp v192, v130, v92 row_shr:2 row_mask:0xf bank_mask:0xf
	v_fmac_f32_dpp v193, v131, v93 row_shr:2 row_mask:0xf bank_mask:0xf
	v_fmac_f32_dpp v194, v132, v94 row_shr:2 row_mask:0xf bank_mask:0xf
	v_fmac_f32_dpp v195, v133, v95 row_shr:2 row_mask:0xf bank_mask:0xf
	v_fmac_f32_dpp v188, v146, v80 row_shl:15 row_mask:0xf bank_mask:0xf
	v_fmac_f32_dpp v189, v147, v81 row_shl:15 row_mask:0xf bank_mask:0xf
	v_fmac_f32_dpp v190, v148, v82 row_shl:15 row_mask:0xf bank_mask:0xf
	v_fmac_f32_dpp v191, v149, v83 row_shl:15 row_mask:0xf bank_mask:0xf
	v_fmac_f32_dpp v192, v134, v96 row_shl:15 row_mask:0xf bank_mask:0xf
	v_fmac_f32_dpp v193, v135, v97 row_shl:15 row_mask:0xf bank_mask:0xf
	v_fmac_f32_dpp v194, v136, v98 row_shl:15 row_mask:0xf bank_mask:0xf
	v_fmac_f32_dpp v195, v137, v99 row_shl:15 row_mask:0xf bank_mask:0xf
	v_fmac_f32_dpp v188, v146, v76 row_shl:14 row_mask:0xf bank_mask:0xf
	v_fmac_f32_dpp v189, v147, v77 row_shl:14 row_mask:0xf bank_mask:0xf
	v_fmac_f32_dpp v190, v148, v78 row_shl:14 row_mask:0xf bank_mask:0xf
	v_fmac_f32_dpp v191, v149, v79 row_shl:14 row_mask:0xf bank_mask:0xf
	v_fmac_f32_dpp v192, v134, v92 row_shl:14 row_mask:0xf bank_mask:0xf
	v_fmac_f32_dpp v193, v135, v93 row_shl:14 row_mask:0xf bank_mask:0xf
	v_fmac_f32_dpp v194, v136, v94 row_shl:14 row_mask:0xf bank_mask:0xf
	v_fmac_f32_dpp v195, v137, v95 row_shl:14 row_mask:0xf bank_mask:0xf
	v_pk_mul_f32 v[196:197], v[188:189], v[216:217] op_sel_hi:[1,0]
	v_pk_mul_f32 v[198:199], v[190:191], v[216:217] op_sel_hi:[1,0]
	v_exp_f32_e32 v196, v196
	v_exp_f32_e32 v197, v197
	v_exp_f32_e32 v198, v198
	v_exp_f32_e32 v199, v199
	v_pk_add_f32 v[196:197], v[196:197], v[214:215] op_sel_hi:[1,0]
	v_pk_add_f32 v[198:199], v[198:199], v[214:215] op_sel_hi:[1,0]
	v_rcp_f32_e32 v196, v196
	v_rcp_f32_e32 v197, v197
	v_rcp_f32_e32 v198, v198
	v_rcp_f32_e32 v199, v199
	v_pk_mul_f32 v[188:189], v[188:189], v[196:197]
	v_pk_mul_f32 v[190:191], v[190:191], v[198:199]
	v_pk_mul_f32 v[188:189], v[188:189], v[192:193]
	v_pk_mul_f32 v[190:191], v[190:191], v[194:195]
	v_cvt_pk_bf16_f32 v146, v188, v189
	v_cvt_pk_bf16_f32 v147, v190, v191
	v_add_u32_e32 v213, 0x37000, v212
	global_load_dwordx4 v[134:137], v213, s[82:83] offset:16
	v_pk_fma_f32 v[188:189], v[126:127], v[84:85], v[88:89]
	v_pk_fma_f32 v[190:191], v[128:129], v[86:87], v[90:91]
	v_pk_fma_f32 v[192:193], v[118:119], v[100:101], v[104:105]
	v_pk_fma_f32 v[194:195], v[120:121], v[102:103], v[106:107]
	v_fmac_f32_dpp v188, v126, v80 row_shr:1 row_mask:0xf bank_mask:0xf
	v_fmac_f32_dpp v189, v127, v81 row_shr:1 row_mask:0xf bank_mask:0xf
	v_fmac_f32_dpp v190, v128, v82 row_shr:1 row_mask:0xf bank_mask:0xf
	v_fmac_f32_dpp v191, v129, v83 row_shr:1 row_mask:0xf bank_mask:0xf
	v_fmac_f32_dpp v192, v118, v96 row_shr:1 row_mask:0xf bank_mask:0xf
	v_fmac_f32_dpp v193, v119, v97 row_shr:1 row_mask:0xf bank_mask:0xf
	v_fmac_f32_dpp v194, v120, v98 row_shr:1 row_mask:0xf bank_mask:0xf
	v_fmac_f32_dpp v195, v121, v99 row_shr:1 row_mask:0xf bank_mask:0xf
	v_fmac_f32_dpp v188, v126, v76 row_shr:2 row_mask:0xf bank_mask:0xf
	v_fmac_f32_dpp v189, v127, v77 row_shr:2 row_mask:0xf bank_mask:0xf
	v_fmac_f32_dpp v190, v128, v78 row_shr:2 row_mask:0xf bank_mask:0xf
	v_fmac_f32_dpp v191, v129, v79 row_shr:2 row_mask:0xf bank_mask:0xf
	v_fmac_f32_dpp v192, v118, v92 row_shr:2 row_mask:0xf bank_mask:0xf
	v_fmac_f32_dpp v193, v119, v93 row_shr:2 row_mask:0xf bank_mask:0xf
	v_fmac_f32_dpp v194, v120, v94 row_shr:2 row_mask:0xf bank_mask:0xf
	v_fmac_f32_dpp v195, v121, v95 row_shr:2 row_mask:0xf bank_mask:0xf
	v_fmac_f32_dpp v188, v138, v80 row_shl:15 row_mask:0xf bank_mask:0xf
	v_fmac_f32_dpp v189, v139, v81 row_shl:15 row_mask:0xf bank_mask:0xf
	v_fmac_f32_dpp v190, v140, v82 row_shl:15 row_mask:0xf bank_mask:0xf
	v_fmac_f32_dpp v191, v141, v83 row_shl:15 row_mask:0xf bank_mask:0xf
	v_fmac_f32_dpp v192, v130, v96 row_shl:15 row_mask:0xf bank_mask:0xf
	v_fmac_f32_dpp v193, v131, v97 row_shl:15 row_mask:0xf bank_mask:0xf
	v_fmac_f32_dpp v194, v132, v98 row_shl:15 row_mask:0xf bank_mask:0xf
	v_fmac_f32_dpp v195, v133, v99 row_shl:15 row_mask:0xf bank_mask:0xf
	v_fmac_f32_dpp v188, v138, v76 row_shl:14 row_mask:0xf bank_mask:0xf
	v_fmac_f32_dpp v189, v139, v77 row_shl:14 row_mask:0xf bank_mask:0xf
	v_fmac_f32_dpp v190, v140, v78 row_shl:14 row_mask:0xf bank_mask:0xf
	v_fmac_f32_dpp v191, v141, v79 row_shl:14 row_mask:0xf bank_mask:0xf
	v_fmac_f32_dpp v192, v130, v92 row_shl:14 row_mask:0xf bank_mask:0xf
	v_fmac_f32_dpp v193, v131, v93 row_shl:14 row_mask:0xf bank_mask:0xf
	v_fmac_f32_dpp v194, v132, v94 row_shl:14 row_mask:0xf bank_mask:0xf
	v_fmac_f32_dpp v195, v133, v95 row_shl:14 row_mask:0xf bank_mask:0xf
	v_pk_mul_f32 v[196:197], v[188:189], v[216:217] op_sel_hi:[1,0]
	v_pk_mul_f32 v[198:199], v[190:191], v[216:217] op_sel_hi:[1,0]
	v_exp_f32_e32 v196, v196
	v_exp_f32_e32 v197, v197
	v_exp_f32_e32 v198, v198
	v_exp_f32_e32 v199, v199
	v_pk_add_f32 v[196:197], v[196:197], v[214:215] op_sel_hi:[1,0]
	v_pk_add_f32 v[198:199], v[198:199], v[214:215] op_sel_hi:[1,0]
	v_rcp_f32_e32 v196, v196
	v_rcp_f32_e32 v197, v197
	v_rcp_f32_e32 v198, v198
	v_rcp_f32_e32 v199, v199
	v_pk_mul_f32 v[188:189], v[188:189], v[196:197]
	v_pk_mul_f32 v[190:191], v[190:191], v[198:199]
	v_pk_mul_f32 v[188:189], v[188:189], v[192:193]
	v_pk_mul_f32 v[190:191], v[190:191], v[194:195]
	v_cvt_pk_bf16_f32 v138, v188, v189
	v_cvt_pk_bf16_f32 v139, v190, v191
	v_add_u32_e32 v213, 0xb000, v212
	global_load_dwordx4 v[130:133], v213, s[84:85] offset:16
	v_pk_fma_f32 v[188:189], v[122:123], v[84:85], v[88:89]
	v_pk_fma_f32 v[190:191], v[124:125], v[86:87], v[90:91]
	v_pk_fma_f32 v[192:193], v[110:111], v[100:101], v[104:105]
	v_pk_fma_f32 v[194:195], v[112:113], v[102:103], v[106:107]
	v_fmac_f32_dpp v188, v122, v80 row_shr:1 row_mask:0xf bank_mask:0xf
	v_fmac_f32_dpp v189, v123, v81 row_shr:1 row_mask:0xf bank_mask:0xf
	v_fmac_f32_dpp v190, v124, v82 row_shr:1 row_mask:0xf bank_mask:0xf
	v_fmac_f32_dpp v191, v125, v83 row_shr:1 row_mask:0xf bank_mask:0xf
	v_fmac_f32_dpp v192, v110, v96 row_shr:1 row_mask:0xf bank_mask:0xf
	v_fmac_f32_dpp v193, v111, v97 row_shr:1 row_mask:0xf bank_mask:0xf
	v_fmac_f32_dpp v194, v112, v98 row_shr:1 row_mask:0xf bank_mask:0xf
	v_fmac_f32_dpp v195, v113, v99 row_shr:1 row_mask:0xf bank_mask:0xf
	v_fmac_f32_dpp v188, v122, v76 row_shr:2 row_mask:0xf bank_mask:0xf
	v_fmac_f32_dpp v189, v123, v77 row_shr:2 row_mask:0xf bank_mask:0xf
	v_fmac_f32_dpp v190, v124, v78 row_shr:2 row_mask:0xf bank_mask:0xf
	v_fmac_f32_dpp v191, v125, v79 row_shr:2 row_mask:0xf bank_mask:0xf
	v_fmac_f32_dpp v192, v110, v92 row_shr:2 row_mask:0xf bank_mask:0xf
	v_fmac_f32_dpp v193, v111, v93 row_shr:2 row_mask:0xf bank_mask:0xf
	v_fmac_f32_dpp v194, v112, v94 row_shr:2 row_mask:0xf bank_mask:0xf
	v_fmac_f32_dpp v195, v113, v95 row_shr:2 row_mask:0xf bank_mask:0xf
	v_fmac_f32_dpp v188, v126, v80 row_shl:15 row_mask:0xf bank_mask:0xf
	v_fmac_f32_dpp v189, v127, v81 row_shl:15 row_mask:0xf bank_mask:0xf
	v_fmac_f32_dpp v190, v128, v82 row_shl:15 row_mask:0xf bank_mask:0xf
	v_fmac_f32_dpp v191, v129, v83 row_shl:15 row_mask:0xf bank_mask:0xf
	v_fmac_f32_dpp v192, v118, v96 row_shl:15 row_mask:0xf bank_mask:0xf
	v_fmac_f32_dpp v193, v119, v97 row_shl:15 row_mask:0xf bank_mask:0xf
	v_fmac_f32_dpp v194, v120, v98 row_shl:15 row_mask:0xf bank_mask:0xf
	v_fmac_f32_dpp v195, v121, v99 row_shl:15 row_mask:0xf bank_mask:0xf
	v_fmac_f32_dpp v188, v126, v76 row_shl:14 row_mask:0xf bank_mask:0xf
	v_fmac_f32_dpp v189, v127, v77 row_shl:14 row_mask:0xf bank_mask:0xf
	v_fmac_f32_dpp v190, v128, v78 row_shl:14 row_mask:0xf bank_mask:0xf
	v_fmac_f32_dpp v191, v129, v79 row_shl:14 row_mask:0xf bank_mask:0xf
	v_fmac_f32_dpp v192, v118, v92 row_shl:14 row_mask:0xf bank_mask:0xf
	v_fmac_f32_dpp v193, v119, v93 row_shl:14 row_mask:0xf bank_mask:0xf
	v_fmac_f32_dpp v194, v120, v94 row_shl:14 row_mask:0xf bank_mask:0xf
	v_fmac_f32_dpp v195, v121, v95 row_shl:14 row_mask:0xf bank_mask:0xf
	v_pk_mul_f32 v[196:197], v[188:189], v[216:217] op_sel_hi:[1,0]
	v_pk_mul_f32 v[198:199], v[190:191], v[216:217] op_sel_hi:[1,0]
	v_exp_f32_e32 v196, v196
	v_exp_f32_e32 v197, v197
	v_exp_f32_e32 v198, v198
	v_exp_f32_e32 v199, v199
	v_pk_add_f32 v[196:197], v[196:197], v[214:215] op_sel_hi:[1,0]
	v_pk_add_f32 v[198:199], v[198:199], v[214:215] op_sel_hi:[1,0]
	v_rcp_f32_e32 v196, v196
	v_rcp_f32_e32 v197, v197
	v_rcp_f32_e32 v198, v198
	v_rcp_f32_e32 v199, v199
	v_pk_mul_f32 v[188:189], v[188:189], v[196:197]
	v_pk_mul_f32 v[190:191], v[190:191], v[198:199]
	v_pk_mul_f32 v[188:189], v[188:189], v[192:193]
	v_pk_mul_f32 v[190:191], v[190:191], v[194:195]
	v_cvt_pk_bf16_f32 v126, v188, v189
	v_cvt_pk_bf16_f32 v127, v190, v191
	v_add_u32_e32 v213, 0x26800, v212
	global_load_dwordx4 v[118:121], v213, s[82:83] offset:16
	v_pk_fma_f32 v[188:189], v[114:115], v[84:85], v[88:89]
	v_pk_fma_f32 v[190:191], v[116:117], v[86:87], v[90:91]
	v_pk_fma_f32 v[192:193], v[68:69], v[100:101], v[104:105]
	v_pk_fma_f32 v[194:195], v[70:71], v[102:103], v[106:107]
	v_fmac_f32_dpp v188, v114, v80 row_shr:1 row_mask:0xf bank_mask:0xf
	v_fmac_f32_dpp v189, v115, v81 row_shr:1 row_mask:0xf bank_mask:0xf
	v_fmac_f32_dpp v190, v116, v82 row_shr:1 row_mask:0xf bank_mask:0xf
	v_fmac_f32_dpp v191, v117, v83 row_shr:1 row_mask:0xf bank_mask:0xf
	v_fmac_f32_dpp v192, v68, v96 row_shr:1 row_mask:0xf bank_mask:0xf
	v_fmac_f32_dpp v193, v69, v97 row_shr:1 row_mask:0xf bank_mask:0xf
	v_fmac_f32_dpp v194, v70, v98 row_shr:1 row_mask:0xf bank_mask:0xf
	v_fmac_f32_dpp v195, v71, v99 row_shr:1 row_mask:0xf bank_mask:0xf
	v_fmac_f32_dpp v188, v114, v76 row_shr:2 row_mask:0xf bank_mask:0xf
	v_fmac_f32_dpp v189, v115, v77 row_shr:2 row_mask:0xf bank_mask:0xf
	v_fmac_f32_dpp v190, v116, v78 row_shr:2 row_mask:0xf bank_mask:0xf
	v_fmac_f32_dpp v191, v117, v79 row_shr:2 row_mask:0xf bank_mask:0xf
	v_fmac_f32_dpp v192, v68, v92 row_shr:2 row_mask:0xf bank_mask:0xf
	v_fmac_f32_dpp v193, v69, v93 row_shr:2 row_mask:0xf bank_mask:0xf
	v_fmac_f32_dpp v194, v70, v94 row_shr:2 row_mask:0xf bank_mask:0xf
	v_fmac_f32_dpp v195, v71, v95 row_shr:2 row_mask:0xf bank_mask:0xf
	v_fmac_f32_dpp v188, v122, v80 row_shl:15 row_mask:0xf bank_mask:0xf
	v_fmac_f32_dpp v189, v123, v81 row_shl:15 row_mask:0xf bank_mask:0xf
	v_fmac_f32_dpp v190, v124, v82 row_shl:15 row_mask:0xf bank_mask:0xf
	v_fmac_f32_dpp v191, v125, v83 row_shl:15 row_mask:0xf bank_mask:0xf
	v_fmac_f32_dpp v192, v110, v96 row_shl:15 row_mask:0xf bank_mask:0xf
	v_fmac_f32_dpp v193, v111, v97 row_shl:15 row_mask:0xf bank_mask:0xf
	v_fmac_f32_dpp v194, v112, v98 row_shl:15 row_mask:0xf bank_mask:0xf
	v_fmac_f32_dpp v195, v113, v99 row_shl:15 row_mask:0xf bank_mask:0xf
	v_fmac_f32_dpp v188, v122, v76 row_shl:14 row_mask:0xf bank_mask:0xf
	v_fmac_f32_dpp v189, v123, v77 row_shl:14 row_mask:0xf bank_mask:0xf
	v_fmac_f32_dpp v190, v124, v78 row_shl:14 row_mask:0xf bank_mask:0xf
	v_fmac_f32_dpp v191, v125, v79 row_shl:14 row_mask:0xf bank_mask:0xf
	v_fmac_f32_dpp v192, v110, v92 row_shl:14 row_mask:0xf bank_mask:0xf
	v_fmac_f32_dpp v193, v111, v93 row_shl:14 row_mask:0xf bank_mask:0xf
	v_fmac_f32_dpp v194, v112, v94 row_shl:14 row_mask:0xf bank_mask:0xf
	v_fmac_f32_dpp v195, v113, v95 row_shl:14 row_mask:0xf bank_mask:0xf
	v_pk_mul_f32 v[196:197], v[188:189], v[216:217] op_sel_hi:[1,0]
	v_pk_mul_f32 v[198:199], v[190:191], v[216:217] op_sel_hi:[1,0]
	v_exp_f32_e32 v196, v196
	v_exp_f32_e32 v197, v197
	v_exp_f32_e32 v198, v198
	v_exp_f32_e32 v199, v199
	v_pk_add_f32 v[196:197], v[196:197], v[214:215] op_sel_hi:[1,0]
	v_pk_add_f32 v[198:199], v[198:199], v[214:215] op_sel_hi:[1,0]
	v_rcp_f32_e32 v196, v196
	v_rcp_f32_e32 v197, v197
	v_rcp_f32_e32 v198, v198
	v_rcp_f32_e32 v199, v199
	v_pk_mul_f32 v[188:189], v[188:189], v[196:197]
	v_pk_mul_f32 v[190:191], v[190:191], v[198:199]
	v_pk_mul_f32 v[188:189], v[188:189], v[192:193]
	v_pk_mul_f32 v[190:191], v[190:191], v[194:195]
	v_cvt_pk_bf16_f32 v122, v188, v189
	v_cvt_pk_bf16_f32 v123, v190, v191
	v_add_u32_e32 v213, 0x31800, v212
	global_load_dwordx4 v[110:113], v213, s[82:83] offset:16
	v_pk_fma_f32 v[188:189], v[72:73], v[84:85], v[88:89]
	v_pk_fma_f32 v[190:191], v[74:75], v[86:87], v[90:91]
	v_pk_fma_f32 v[192:193], v[64:65], v[100:101], v[104:105]
	v_pk_fma_f32 v[194:195], v[66:67], v[102:103], v[106:107]
	v_fmac_f32_dpp v188, v72, v80 row_shr:1 row_mask:0xf bank_mask:0xf
	v_fmac_f32_dpp v189, v73, v81 row_shr:1 row_mask:0xf bank_mask:0xf
	v_fmac_f32_dpp v190, v74, v82 row_shr:1 row_mask:0xf bank_mask:0xf
	v_fmac_f32_dpp v191, v75, v83 row_shr:1 row_mask:0xf bank_mask:0xf
	v_fmac_f32_dpp v192, v64, v96 row_shr:1 row_mask:0xf bank_mask:0xf
	v_fmac_f32_dpp v193, v65, v97 row_shr:1 row_mask:0xf bank_mask:0xf
	v_fmac_f32_dpp v194, v66, v98 row_shr:1 row_mask:0xf bank_mask:0xf
	v_fmac_f32_dpp v195, v67, v99 row_shr:1 row_mask:0xf bank_mask:0xf
	v_fmac_f32_dpp v188, v72, v76 row_shr:2 row_mask:0xf bank_mask:0xf
	v_fmac_f32_dpp v189, v73, v77 row_shr:2 row_mask:0xf bank_mask:0xf
	v_fmac_f32_dpp v190, v74, v78 row_shr:2 row_mask:0xf bank_mask:0xf
	v_fmac_f32_dpp v191, v75, v79 row_shr:2 row_mask:0xf bank_mask:0xf
	v_fmac_f32_dpp v192, v64, v92 row_shr:2 row_mask:0xf bank_mask:0xf
	v_fmac_f32_dpp v193, v65, v93 row_shr:2 row_mask:0xf bank_mask:0xf
	v_fmac_f32_dpp v194, v66, v94 row_shr:2 row_mask:0xf bank_mask:0xf
	v_fmac_f32_dpp v195, v67, v95 row_shr:2 row_mask:0xf bank_mask:0xf
	v_fmac_f32_dpp v188, v114, v80 row_shl:15 row_mask:0xf bank_mask:0xf
	v_fmac_f32_dpp v189, v115, v81 row_shl:15 row_mask:0xf bank_mask:0xf
	v_fmac_f32_dpp v190, v116, v82 row_shl:15 row_mask:0xf bank_mask:0xf
	v_fmac_f32_dpp v191, v117, v83 row_shl:15 row_mask:0xf bank_mask:0xf
	v_fmac_f32_dpp v192, v68, v96 row_shl:15 row_mask:0xf bank_mask:0xf
	v_fmac_f32_dpp v193, v69, v97 row_shl:15 row_mask:0xf bank_mask:0xf
	v_fmac_f32_dpp v194, v70, v98 row_shl:15 row_mask:0xf bank_mask:0xf
	v_fmac_f32_dpp v195, v71, v99 row_shl:15 row_mask:0xf bank_mask:0xf
	v_fmac_f32_dpp v188, v114, v76 row_shl:14 row_mask:0xf bank_mask:0xf
	v_fmac_f32_dpp v189, v115, v77 row_shl:14 row_mask:0xf bank_mask:0xf
	v_fmac_f32_dpp v190, v116, v78 row_shl:14 row_mask:0xf bank_mask:0xf
	v_fmac_f32_dpp v191, v117, v79 row_shl:14 row_mask:0xf bank_mask:0xf
	v_fmac_f32_dpp v192, v68, v92 row_shl:14 row_mask:0xf bank_mask:0xf
	v_fmac_f32_dpp v193, v69, v93 row_shl:14 row_mask:0xf bank_mask:0xf
	v_fmac_f32_dpp v194, v70, v94 row_shl:14 row_mask:0xf bank_mask:0xf
	v_fmac_f32_dpp v195, v71, v95 row_shl:14 row_mask:0xf bank_mask:0xf
	v_pk_mul_f32 v[196:197], v[188:189], v[216:217] op_sel_hi:[1,0]
	v_pk_mul_f32 v[198:199], v[190:191], v[216:217] op_sel_hi:[1,0]
	v_exp_f32_e32 v196, v196
	v_exp_f32_e32 v197, v197
	v_exp_f32_e32 v198, v198
	v_exp_f32_e32 v199, v199
	v_pk_add_f32 v[196:197], v[196:197], v[214:215] op_sel_hi:[1,0]
	v_pk_add_f32 v[198:199], v[198:199], v[214:215] op_sel_hi:[1,0]
	v_rcp_f32_e32 v196, v196
	v_rcp_f32_e32 v197, v197
	v_rcp_f32_e32 v198, v198
	v_rcp_f32_e32 v199, v199
	v_pk_mul_f32 v[188:189], v[188:189], v[196:197]
	v_pk_mul_f32 v[190:191], v[190:191], v[198:199]
	v_pk_mul_f32 v[188:189], v[188:189], v[192:193]
	v_pk_mul_f32 v[190:191], v[190:191], v[194:195]
	v_cvt_pk_bf16_f32 v114, v188, v189
	v_cvt_pk_bf16_f32 v115, v190, v191
	s_waitcnt vmcnt(0)
	v_pk_fma_f32 v[188:189], v[60:61], v[134:135], v[130:131]
	v_pk_fma_f32 v[190:191], v[62:63], v[136:137], v[132:133]
	v_pk_fma_f32 v[192:193], v[56:57], v[204:205], v[208:209]
	v_pk_fma_f32 v[194:195], v[58:59], v[206:207], v[210:211]
	v_fmac_f32_dpp v188, v60, v142 row_shr:1 row_mask:0xf bank_mask:0xf
	v_fmac_f32_dpp v189, v61, v143 row_shr:1 row_mask:0xf bank_mask:0xf
	v_fmac_f32_dpp v190, v62, v144 row_shr:1 row_mask:0xf bank_mask:0xf
	v_fmac_f32_dpp v191, v63, v145 row_shr:1 row_mask:0xf bank_mask:0xf
	v_fmac_f32_dpp v192, v56, v110 row_shr:1 row_mask:0xf bank_mask:0xf
	v_fmac_f32_dpp v193, v57, v111 row_shr:1 row_mask:0xf bank_mask:0xf
	v_fmac_f32_dpp v194, v58, v112 row_shr:1 row_mask:0xf bank_mask:0xf
	v_fmac_f32_dpp v195, v59, v113 row_shr:1 row_mask:0xf bank_mask:0xf
	v_fmac_f32_dpp v188, v60, v154 row_shr:2 row_mask:0xf bank_mask:0xf
	v_fmac_f32_dpp v189, v61, v155 row_shr:2 row_mask:0xf bank_mask:0xf
	v_fmac_f32_dpp v190, v62, v156 row_shr:2 row_mask:0xf bank_mask:0xf
	v_fmac_f32_dpp v191, v63, v157 row_shr:2 row_mask:0xf bank_mask:0xf
	v_fmac_f32_dpp v192, v56, v118 row_shr:2 row_mask:0xf bank_mask:0xf
	v_fmac_f32_dpp v193, v57, v119 row_shr:2 row_mask:0xf bank_mask:0xf
	v_fmac_f32_dpp v194, v58, v120 row_shr:2 row_mask:0xf bank_mask:0xf
	v_fmac_f32_dpp v195, v59, v121 row_shr:2 row_mask:0xf bank_mask:0xf
	v_pk_mul_f32 v[196:197], v[188:189], v[216:217] op_sel_hi:[1,0]
	v_pk_mul_f32 v[198:199], v[190:191], v[216:217] op_sel_hi:[1,0]
	v_exp_f32_e32 v196, v196
	v_exp_f32_e32 v197, v197
	v_exp_f32_e32 v198, v198
	v_exp_f32_e32 v199, v199
	v_pk_add_f32 v[196:197], v[196:197], v[214:215] op_sel_hi:[1,0]
	v_pk_add_f32 v[198:199], v[198:199], v[214:215] op_sel_hi:[1,0]
	v_rcp_f32_e32 v196, v196
	v_rcp_f32_e32 v197, v197
	v_rcp_f32_e32 v198, v198
	v_rcp_f32_e32 v199, v199
	v_pk_mul_f32 v[188:189], v[188:189], v[196:197]
	v_pk_mul_f32 v[190:191], v[190:191], v[198:199]
	v_pk_mul_f32 v[188:189], v[188:189], v[192:193]
	v_pk_mul_f32 v[190:191], v[190:191], v[194:195]
	v_cvt_pk_bf16_f32 v202, v188, v189
	v_cvt_pk_bf16_f32 v203, v190, v191
	s_mov_b64 exec, vcc
	global_store_dwordx4 v215, v[200:203], s[96:97] nt
	s_mov_b64 exec, -1
	v_pk_fma_f32 v[188:189], v[52:53], v[134:135], v[130:131]
	v_pk_fma_f32 v[190:191], v[54:55], v[136:137], v[132:133]
	v_pk_fma_f32 v[192:193], v[44:45], v[204:205], v[208:209]
	v_pk_fma_f32 v[194:195], v[46:47], v[206:207], v[210:211]
	v_fmac_f32_dpp v188, v52, v142 row_shr:1 row_mask:0xf bank_mask:0xf
	v_fmac_f32_dpp v189, v53, v143 row_shr:1 row_mask:0xf bank_mask:0xf
	v_fmac_f32_dpp v190, v54, v144 row_shr:1 row_mask:0xf bank_mask:0xf
	v_fmac_f32_dpp v191, v55, v145 row_shr:1 row_mask:0xf bank_mask:0xf
	v_fmac_f32_dpp v192, v44, v110 row_shr:1 row_mask:0xf bank_mask:0xf
	v_fmac_f32_dpp v193, v45, v111 row_shr:1 row_mask:0xf bank_mask:0xf
	v_fmac_f32_dpp v194, v46, v112 row_shr:1 row_mask:0xf bank_mask:0xf
	v_fmac_f32_dpp v195, v47, v113 row_shr:1 row_mask:0xf bank_mask:0xf
	v_fmac_f32_dpp v188, v52, v154 row_shr:2 row_mask:0xf bank_mask:0xf
	v_fmac_f32_dpp v189, v53, v155 row_shr:2 row_mask:0xf bank_mask:0xf
	v_fmac_f32_dpp v190, v54, v156 row_shr:2 row_mask:0xf bank_mask:0xf
	v_fmac_f32_dpp v191, v55, v157 row_shr:2 row_mask:0xf bank_mask:0xf
	v_fmac_f32_dpp v192, v44, v118 row_shr:2 row_mask:0xf bank_mask:0xf
	v_fmac_f32_dpp v193, v45, v119 row_shr:2 row_mask:0xf bank_mask:0xf
	v_fmac_f32_dpp v194, v46, v120 row_shr:2 row_mask:0xf bank_mask:0xf
	v_fmac_f32_dpp v195, v47, v121 row_shr:2 row_mask:0xf bank_mask:0xf
	v_fmac_f32_dpp v188, v60, v142 row_shl:15 row_mask:0xf bank_mask:0xf
	v_fmac_f32_dpp v189, v61, v143 row_shl:15 row_mask:0xf bank_mask:0xf
	v_fmac_f32_dpp v190, v62, v144 row_shl:15 row_mask:0xf bank_mask:0xf
	v_fmac_f32_dpp v191, v63, v145 row_shl:15 row_mask:0xf bank_mask:0xf
	v_fmac_f32_dpp v192, v56, v110 row_shl:15 row_mask:0xf bank_mask:0xf
	v_fmac_f32_dpp v193, v57, v111 row_shl:15 row_mask:0xf bank_mask:0xf
	v_fmac_f32_dpp v194, v58, v112 row_shl:15 row_mask:0xf bank_mask:0xf
	v_fmac_f32_dpp v195, v59, v113 row_shl:15 row_mask:0xf bank_mask:0xf
	v_fmac_f32_dpp v188, v60, v154 row_shl:14 row_mask:0xf bank_mask:0xf
	v_fmac_f32_dpp v189, v61, v155 row_shl:14 row_mask:0xf bank_mask:0xf
	v_fmac_f32_dpp v190, v62, v156 row_shl:14 row_mask:0xf bank_mask:0xf
	v_fmac_f32_dpp v191, v63, v157 row_shl:14 row_mask:0xf bank_mask:0xf
	v_fmac_f32_dpp v192, v56, v118 row_shl:14 row_mask:0xf bank_mask:0xf
	v_fmac_f32_dpp v193, v57, v119 row_shl:14 row_mask:0xf bank_mask:0xf
	v_fmac_f32_dpp v194, v58, v120 row_shl:14 row_mask:0xf bank_mask:0xf
	v_fmac_f32_dpp v195, v59, v121 row_shl:14 row_mask:0xf bank_mask:0xf
	v_pk_mul_f32 v[196:197], v[188:189], v[216:217] op_sel_hi:[1,0]
	v_pk_mul_f32 v[198:199], v[190:191], v[216:217] op_sel_hi:[1,0]
	v_exp_f32_e32 v196, v196
	v_exp_f32_e32 v197, v197
	v_exp_f32_e32 v198, v198
	v_exp_f32_e32 v199, v199
	v_pk_add_f32 v[196:197], v[196:197], v[214:215] op_sel_hi:[1,0]
	v_pk_add_f32 v[198:199], v[198:199], v[214:215] op_sel_hi:[1,0]
	v_rcp_f32_e32 v196, v196
	v_rcp_f32_e32 v197, v197
	v_rcp_f32_e32 v198, v198
	v_rcp_f32_e32 v199, v199
	v_pk_mul_f32 v[188:189], v[188:189], v[196:197]
	v_pk_mul_f32 v[190:191], v[190:191], v[198:199]
	v_pk_mul_f32 v[188:189], v[188:189], v[192:193]
	v_pk_mul_f32 v[190:191], v[190:191], v[194:195]
	v_cvt_pk_bf16_f32 v160, v188, v189
	v_cvt_pk_bf16_f32 v161, v190, v191
	v_add_u32_e32 v213, 0x2c000, v215
	global_store_dwordx4 v213, v[158:161], s[96:97] nt
	v_pk_fma_f32 v[188:189], v[48:49], v[134:135], v[130:131]
	v_pk_fma_f32 v[190:191], v[50:51], v[136:137], v[132:133]
	v_pk_fma_f32 v[192:193], v[36:37], v[204:205], v[208:209]
	v_pk_fma_f32 v[194:195], v[38:39], v[206:207], v[210:211]
	v_fmac_f32_dpp v188, v48, v142 row_shr:1 row_mask:0xf bank_mask:0xf
	v_fmac_f32_dpp v189, v49, v143 row_shr:1 row_mask:0xf bank_mask:0xf
	v_fmac_f32_dpp v190, v50, v144 row_shr:1 row_mask:0xf bank_mask:0xf
	v_fmac_f32_dpp v191, v51, v145 row_shr:1 row_mask:0xf bank_mask:0xf
	v_fmac_f32_dpp v192, v36, v110 row_shr:1 row_mask:0xf bank_mask:0xf
	v_fmac_f32_dpp v193, v37, v111 row_shr:1 row_mask:0xf bank_mask:0xf
	v_fmac_f32_dpp v194, v38, v112 row_shr:1 row_mask:0xf bank_mask:0xf
	v_fmac_f32_dpp v195, v39, v113 row_shr:1 row_mask:0xf bank_mask:0xf
	v_fmac_f32_dpp v188, v48, v154 row_shr:2 row_mask:0xf bank_mask:0xf
	v_fmac_f32_dpp v189, v49, v155 row_shr:2 row_mask:0xf bank_mask:0xf
	v_fmac_f32_dpp v190, v50, v156 row_shr:2 row_mask:0xf bank_mask:0xf
	v_fmac_f32_dpp v191, v51, v157 row_shr:2 row_mask:0xf bank_mask:0xf
	v_fmac_f32_dpp v192, v36, v118 row_shr:2 row_mask:0xf bank_mask:0xf
	v_fmac_f32_dpp v193, v37, v119 row_shr:2 row_mask:0xf bank_mask:0xf
	v_fmac_f32_dpp v194, v38, v120 row_shr:2 row_mask:0xf bank_mask:0xf
	v_fmac_f32_dpp v195, v39, v121 row_shr:2 row_mask:0xf bank_mask:0xf
	v_fmac_f32_dpp v188, v52, v142 row_shl:15 row_mask:0xf bank_mask:0xf
	v_fmac_f32_dpp v189, v53, v143 row_shl:15 row_mask:0xf bank_mask:0xf
	v_fmac_f32_dpp v190, v54, v144 row_shl:15 row_mask:0xf bank_mask:0xf
	v_fmac_f32_dpp v191, v55, v145 row_shl:15 row_mask:0xf bank_mask:0xf
	v_fmac_f32_dpp v192, v44, v110 row_shl:15 row_mask:0xf bank_mask:0xf
	v_fmac_f32_dpp v193, v45, v111 row_shl:15 row_mask:0xf bank_mask:0xf
	v_fmac_f32_dpp v194, v46, v112 row_shl:15 row_mask:0xf bank_mask:0xf
	v_fmac_f32_dpp v195, v47, v113 row_shl:15 row_mask:0xf bank_mask:0xf
	v_fmac_f32_dpp v188, v52, v154 row_shl:14 row_mask:0xf bank_mask:0xf
	v_fmac_f32_dpp v189, v53, v155 row_shl:14 row_mask:0xf bank_mask:0xf
	v_fmac_f32_dpp v190, v54, v156 row_shl:14 row_mask:0xf bank_mask:0xf
	v_fmac_f32_dpp v191, v55, v157 row_shl:14 row_mask:0xf bank_mask:0xf
	v_fmac_f32_dpp v192, v44, v118 row_shl:14 row_mask:0xf bank_mask:0xf
	v_fmac_f32_dpp v193, v45, v119 row_shl:14 row_mask:0xf bank_mask:0xf
	v_fmac_f32_dpp v194, v46, v120 row_shl:14 row_mask:0xf bank_mask:0xf
	v_fmac_f32_dpp v195, v47, v121 row_shl:14 row_mask:0xf bank_mask:0xf
	v_pk_mul_f32 v[196:197], v[188:189], v[216:217] op_sel_hi:[1,0]
	v_pk_mul_f32 v[198:199], v[190:191], v[216:217] op_sel_hi:[1,0]
	v_exp_f32_e32 v196, v196
	v_exp_f32_e32 v197, v197
	v_exp_f32_e32 v198, v198
	v_exp_f32_e32 v199, v199
	v_pk_add_f32 v[196:197], v[196:197], v[214:215] op_sel_hi:[1,0]
	v_pk_add_f32 v[198:199], v[198:199], v[214:215] op_sel_hi:[1,0]
	v_rcp_f32_e32 v196, v196
	v_rcp_f32_e32 v197, v197
	v_rcp_f32_e32 v198, v198
	v_rcp_f32_e32 v199, v199
	v_pk_mul_f32 v[188:189], v[188:189], v[196:197]
	v_pk_mul_f32 v[190:191], v[190:191], v[198:199]
	v_pk_mul_f32 v[188:189], v[188:189], v[192:193]
	v_pk_mul_f32 v[190:191], v[190:191], v[194:195]
	v_cvt_pk_bf16_f32 v152, v188, v189
	v_cvt_pk_bf16_f32 v153, v190, v191
	v_add_u32_e32 v213, 0x58000, v215
	global_store_dwordx4 v213, v[150:153], s[96:97] nt
	v_pk_fma_f32 v[188:189], v[40:41], v[134:135], v[130:131]
	v_pk_fma_f32 v[190:191], v[42:43], v[136:137], v[132:133]
	v_pk_fma_f32 v[192:193], v[32:33], v[204:205], v[208:209]
	v_pk_fma_f32 v[194:195], v[34:35], v[206:207], v[210:211]
	v_fmac_f32_dpp v188, v40, v142 row_shr:1 row_mask:0xf bank_mask:0xf
	v_fmac_f32_dpp v189, v41, v143 row_shr:1 row_mask:0xf bank_mask:0xf
	v_fmac_f32_dpp v190, v42, v144 row_shr:1 row_mask:0xf bank_mask:0xf
	v_fmac_f32_dpp v191, v43, v145 row_shr:1 row_mask:0xf bank_mask:0xf
	v_fmac_f32_dpp v192, v32, v110 row_shr:1 row_mask:0xf bank_mask:0xf
	v_fmac_f32_dpp v193, v33, v111 row_shr:1 row_mask:0xf bank_mask:0xf
	v_fmac_f32_dpp v194, v34, v112 row_shr:1 row_mask:0xf bank_mask:0xf
	v_fmac_f32_dpp v195, v35, v113 row_shr:1 row_mask:0xf bank_mask:0xf
	v_fmac_f32_dpp v188, v40, v154 row_shr:2 row_mask:0xf bank_mask:0xf
	v_fmac_f32_dpp v189, v41, v155 row_shr:2 row_mask:0xf bank_mask:0xf
	v_fmac_f32_dpp v190, v42, v156 row_shr:2 row_mask:0xf bank_mask:0xf
	v_fmac_f32_dpp v191, v43, v157 row_shr:2 row_mask:0xf bank_mask:0xf
	v_fmac_f32_dpp v192, v32, v118 row_shr:2 row_mask:0xf bank_mask:0xf
	v_fmac_f32_dpp v193, v33, v119 row_shr:2 row_mask:0xf bank_mask:0xf
	v_fmac_f32_dpp v194, v34, v120 row_shr:2 row_mask:0xf bank_mask:0xf
	v_fmac_f32_dpp v195, v35, v121 row_shr:2 row_mask:0xf bank_mask:0xf
	v_fmac_f32_dpp v188, v48, v142 row_shl:15 row_mask:0xf bank_mask:0xf
	v_fmac_f32_dpp v189, v49, v143 row_shl:15 row_mask:0xf bank_mask:0xf
	v_fmac_f32_dpp v190, v50, v144 row_shl:15 row_mask:0xf bank_mask:0xf
	v_fmac_f32_dpp v191, v51, v145 row_shl:15 row_mask:0xf bank_mask:0xf
	v_fmac_f32_dpp v192, v36, v110 row_shl:15 row_mask:0xf bank_mask:0xf
	v_fmac_f32_dpp v193, v37, v111 row_shl:15 row_mask:0xf bank_mask:0xf
	v_fmac_f32_dpp v194, v38, v112 row_shl:15 row_mask:0xf bank_mask:0xf
	v_fmac_f32_dpp v195, v39, v113 row_shl:15 row_mask:0xf bank_mask:0xf
	v_fmac_f32_dpp v188, v48, v154 row_shl:14 row_mask:0xf bank_mask:0xf
	v_fmac_f32_dpp v189, v49, v155 row_shl:14 row_mask:0xf bank_mask:0xf
	v_fmac_f32_dpp v190, v50, v156 row_shl:14 row_mask:0xf bank_mask:0xf
	v_fmac_f32_dpp v191, v51, v157 row_shl:14 row_mask:0xf bank_mask:0xf
	v_fmac_f32_dpp v192, v36, v118 row_shl:14 row_mask:0xf bank_mask:0xf
	v_fmac_f32_dpp v193, v37, v119 row_shl:14 row_mask:0xf bank_mask:0xf
	v_fmac_f32_dpp v194, v38, v120 row_shl:14 row_mask:0xf bank_mask:0xf
	v_fmac_f32_dpp v195, v39, v121 row_shl:14 row_mask:0xf bank_mask:0xf
	v_pk_mul_f32 v[196:197], v[188:189], v[216:217] op_sel_hi:[1,0]
	v_pk_mul_f32 v[198:199], v[190:191], v[216:217] op_sel_hi:[1,0]
	v_exp_f32_e32 v196, v196
	v_exp_f32_e32 v197, v197
	v_exp_f32_e32 v198, v198
	v_exp_f32_e32 v199, v199
	v_pk_add_f32 v[196:197], v[196:197], v[214:215] op_sel_hi:[1,0]
	v_pk_add_f32 v[198:199], v[198:199], v[214:215] op_sel_hi:[1,0]
	v_rcp_f32_e32 v196, v196
	v_rcp_f32_e32 v197, v197
	v_rcp_f32_e32 v198, v198
	v_rcp_f32_e32 v199, v199
	v_pk_mul_f32 v[188:189], v[188:189], v[196:197]
	v_pk_mul_f32 v[190:191], v[190:191], v[198:199]
	v_pk_mul_f32 v[188:189], v[188:189], v[192:193]
	v_pk_mul_f32 v[190:191], v[190:191], v[194:195]
	v_cvt_pk_bf16_f32 v148, v188, v189
	v_cvt_pk_bf16_f32 v149, v190, v191
	v_add_u32_e32 v213, 0x84000, v215
	global_store_dwordx4 v213, v[146:149], s[96:97] nt
	v_pk_fma_f32 v[188:189], v[28:29], v[134:135], v[130:131]
	v_pk_fma_f32 v[190:191], v[30:31], v[136:137], v[132:133]
	v_pk_fma_f32 v[192:193], v[16:17], v[204:205], v[208:209]
	v_pk_fma_f32 v[194:195], v[18:19], v[206:207], v[210:211]
	v_fmac_f32_dpp v188, v28, v142 row_shr:1 row_mask:0xf bank_mask:0xf
	v_fmac_f32_dpp v189, v29, v143 row_shr:1 row_mask:0xf bank_mask:0xf
	v_fmac_f32_dpp v190, v30, v144 row_shr:1 row_mask:0xf bank_mask:0xf
	v_fmac_f32_dpp v191, v31, v145 row_shr:1 row_mask:0xf bank_mask:0xf
	v_fmac_f32_dpp v192, v16, v110 row_shr:1 row_mask:0xf bank_mask:0xf
	v_fmac_f32_dpp v193, v17, v111 row_shr:1 row_mask:0xf bank_mask:0xf
	v_fmac_f32_dpp v194, v18, v112 row_shr:1 row_mask:0xf bank_mask:0xf
	v_fmac_f32_dpp v195, v19, v113 row_shr:1 row_mask:0xf bank_mask:0xf
	v_fmac_f32_dpp v188, v28, v154 row_shr:2 row_mask:0xf bank_mask:0xf
	v_fmac_f32_dpp v189, v29, v155 row_shr:2 row_mask:0xf bank_mask:0xf
	v_fmac_f32_dpp v190, v30, v156 row_shr:2 row_mask:0xf bank_mask:0xf
	v_fmac_f32_dpp v191, v31, v157 row_shr:2 row_mask:0xf bank_mask:0xf
	v_fmac_f32_dpp v192, v16, v118 row_shr:2 row_mask:0xf bank_mask:0xf
	v_fmac_f32_dpp v193, v17, v119 row_shr:2 row_mask:0xf bank_mask:0xf
	v_fmac_f32_dpp v194, v18, v120 row_shr:2 row_mask:0xf bank_mask:0xf
	v_fmac_f32_dpp v195, v19, v121 row_shr:2 row_mask:0xf bank_mask:0xf
	v_fmac_f32_dpp v188, v40, v142 row_shl:15 row_mask:0xf bank_mask:0xf
	v_fmac_f32_dpp v189, v41, v143 row_shl:15 row_mask:0xf bank_mask:0xf
	v_fmac_f32_dpp v190, v42, v144 row_shl:15 row_mask:0xf bank_mask:0xf
	v_fmac_f32_dpp v191, v43, v145 row_shl:15 row_mask:0xf bank_mask:0xf
	v_fmac_f32_dpp v192, v32, v110 row_shl:15 row_mask:0xf bank_mask:0xf
	v_fmac_f32_dpp v193, v33, v111 row_shl:15 row_mask:0xf bank_mask:0xf
	v_fmac_f32_dpp v194, v34, v112 row_shl:15 row_mask:0xf bank_mask:0xf
	v_fmac_f32_dpp v195, v35, v113 row_shl:15 row_mask:0xf bank_mask:0xf
	v_fmac_f32_dpp v188, v40, v154 row_shl:14 row_mask:0xf bank_mask:0xf
	v_fmac_f32_dpp v189, v41, v155 row_shl:14 row_mask:0xf bank_mask:0xf
	v_fmac_f32_dpp v190, v42, v156 row_shl:14 row_mask:0xf bank_mask:0xf
	v_fmac_f32_dpp v191, v43, v157 row_shl:14 row_mask:0xf bank_mask:0xf
	v_fmac_f32_dpp v192, v32, v118 row_shl:14 row_mask:0xf bank_mask:0xf
	v_fmac_f32_dpp v193, v33, v119 row_shl:14 row_mask:0xf bank_mask:0xf
	v_fmac_f32_dpp v194, v34, v120 row_shl:14 row_mask:0xf bank_mask:0xf
	v_fmac_f32_dpp v195, v35, v121 row_shl:14 row_mask:0xf bank_mask:0xf
	v_pk_mul_f32 v[196:197], v[188:189], v[216:217] op_sel_hi:[1,0]
	v_pk_mul_f32 v[198:199], v[190:191], v[216:217] op_sel_hi:[1,0]
	v_exp_f32_e32 v196, v196
	v_exp_f32_e32 v197, v197
	v_exp_f32_e32 v198, v198
	v_exp_f32_e32 v199, v199
	v_pk_add_f32 v[196:197], v[196:197], v[214:215] op_sel_hi:[1,0]
	v_pk_add_f32 v[198:199], v[198:199], v[214:215] op_sel_hi:[1,0]
	v_rcp_f32_e32 v196, v196
	v_rcp_f32_e32 v197, v197
	v_rcp_f32_e32 v198, v198
	v_rcp_f32_e32 v199, v199
	v_pk_mul_f32 v[188:189], v[188:189], v[196:197]
	v_pk_mul_f32 v[190:191], v[190:191], v[198:199]
	v_pk_mul_f32 v[188:189], v[188:189], v[192:193]
	v_pk_mul_f32 v[190:191], v[190:191], v[194:195]
	v_cvt_pk_bf16_f32 v140, v188, v189
	v_cvt_pk_bf16_f32 v141, v190, v191
	v_add_u32_e32 v213, 0xb0000, v215
	global_store_dwordx4 v213, v[138:141], s[96:97] nt
	v_pk_fma_f32 v[188:189], v[24:25], v[134:135], v[130:131]
	v_pk_fma_f32 v[190:191], v[26:27], v[136:137], v[132:133]
	v_pk_fma_f32 v[192:193], v[12:13], v[204:205], v[208:209]
	v_pk_fma_f32 v[194:195], v[14:15], v[206:207], v[210:211]
	v_fmac_f32_dpp v188, v24, v142 row_shr:1 row_mask:0xf bank_mask:0xf
	v_fmac_f32_dpp v189, v25, v143 row_shr:1 row_mask:0xf bank_mask:0xf
	v_fmac_f32_dpp v190, v26, v144 row_shr:1 row_mask:0xf bank_mask:0xf
	v_fmac_f32_dpp v191, v27, v145 row_shr:1 row_mask:0xf bank_mask:0xf
	v_fmac_f32_dpp v192, v12, v110 row_shr:1 row_mask:0xf bank_mask:0xf
	v_fmac_f32_dpp v193, v13, v111 row_shr:1 row_mask:0xf bank_mask:0xf
	v_fmac_f32_dpp v194, v14, v112 row_shr:1 row_mask:0xf bank_mask:0xf
	v_fmac_f32_dpp v195, v15, v113 row_shr:1 row_mask:0xf bank_mask:0xf
	v_fmac_f32_dpp v188, v24, v154 row_shr:2 row_mask:0xf bank_mask:0xf
	v_fmac_f32_dpp v189, v25, v155 row_shr:2 row_mask:0xf bank_mask:0xf
	v_fmac_f32_dpp v190, v26, v156 row_shr:2 row_mask:0xf bank_mask:0xf
	v_fmac_f32_dpp v191, v27, v157 row_shr:2 row_mask:0xf bank_mask:0xf
	v_fmac_f32_dpp v192, v12, v118 row_shr:2 row_mask:0xf bank_mask:0xf
	v_fmac_f32_dpp v193, v13, v119 row_shr:2 row_mask:0xf bank_mask:0xf
	v_fmac_f32_dpp v194, v14, v120 row_shr:2 row_mask:0xf bank_mask:0xf
	v_fmac_f32_dpp v195, v15, v121 row_shr:2 row_mask:0xf bank_mask:0xf
	v_fmac_f32_dpp v188, v28, v142 row_shl:15 row_mask:0xf bank_mask:0xf
	v_fmac_f32_dpp v189, v29, v143 row_shl:15 row_mask:0xf bank_mask:0xf
	v_fmac_f32_dpp v190, v30, v144 row_shl:15 row_mask:0xf bank_mask:0xf
	v_fmac_f32_dpp v191, v31, v145 row_shl:15 row_mask:0xf bank_mask:0xf
	v_fmac_f32_dpp v192, v16, v110 row_shl:15 row_mask:0xf bank_mask:0xf
	v_fmac_f32_dpp v193, v17, v111 row_shl:15 row_mask:0xf bank_mask:0xf
	v_fmac_f32_dpp v194, v18, v112 row_shl:15 row_mask:0xf bank_mask:0xf
	v_fmac_f32_dpp v195, v19, v113 row_shl:15 row_mask:0xf bank_mask:0xf
	v_fmac_f32_dpp v188, v28, v154 row_shl:14 row_mask:0xf bank_mask:0xf
	v_fmac_f32_dpp v189, v29, v155 row_shl:14 row_mask:0xf bank_mask:0xf
	v_fmac_f32_dpp v190, v30, v156 row_shl:14 row_mask:0xf bank_mask:0xf
	v_fmac_f32_dpp v191, v31, v157 row_shl:14 row_mask:0xf bank_mask:0xf
	v_fmac_f32_dpp v192, v16, v118 row_shl:14 row_mask:0xf bank_mask:0xf
	v_fmac_f32_dpp v193, v17, v119 row_shl:14 row_mask:0xf bank_mask:0xf
	v_fmac_f32_dpp v194, v18, v120 row_shl:14 row_mask:0xf bank_mask:0xf
	v_fmac_f32_dpp v195, v19, v121 row_shl:14 row_mask:0xf bank_mask:0xf
	v_pk_mul_f32 v[196:197], v[188:189], v[216:217] op_sel_hi:[1,0]
	v_pk_mul_f32 v[198:199], v[190:191], v[216:217] op_sel_hi:[1,0]
	v_exp_f32_e32 v196, v196
	v_exp_f32_e32 v197, v197
	v_exp_f32_e32 v198, v198
	v_exp_f32_e32 v199, v199
	v_pk_add_f32 v[196:197], v[196:197], v[214:215] op_sel_hi:[1,0]
	v_pk_add_f32 v[198:199], v[198:199], v[214:215] op_sel_hi:[1,0]
	v_rcp_f32_e32 v196, v196
	v_rcp_f32_e32 v197, v197
	v_rcp_f32_e32 v198, v198
	v_rcp_f32_e32 v199, v199
	v_pk_mul_f32 v[188:189], v[188:189], v[196:197]
	v_pk_mul_f32 v[190:191], v[190:191], v[198:199]
	v_pk_mul_f32 v[188:189], v[188:189], v[192:193]
	v_pk_mul_f32 v[190:191], v[190:191], v[194:195]
	v_cvt_pk_bf16_f32 v128, v188, v189
	v_cvt_pk_bf16_f32 v129, v190, v191
	v_add_u32_e32 v213, 0xdc000, v215
	global_store_dwordx4 v213, v[126:129], s[96:97] nt
	v_pk_fma_f32 v[188:189], v[20:21], v[134:135], v[130:131]
	v_pk_fma_f32 v[190:191], v[22:23], v[136:137], v[132:133]
	v_pk_fma_f32 v[192:193], v[8:9], v[204:205], v[208:209]
	v_pk_fma_f32 v[194:195], v[10:11], v[206:207], v[210:211]
	v_fmac_f32_dpp v188, v20, v142 row_shr:1 row_mask:0xf bank_mask:0xf
	v_fmac_f32_dpp v189, v21, v143 row_shr:1 row_mask:0xf bank_mask:0xf
	v_fmac_f32_dpp v190, v22, v144 row_shr:1 row_mask:0xf bank_mask:0xf
	v_fmac_f32_dpp v191, v23, v145 row_shr:1 row_mask:0xf bank_mask:0xf
	v_fmac_f32_dpp v192, v8, v110 row_shr:1 row_mask:0xf bank_mask:0xf
	v_fmac_f32_dpp v193, v9, v111 row_shr:1 row_mask:0xf bank_mask:0xf
	v_fmac_f32_dpp v194, v10, v112 row_shr:1 row_mask:0xf bank_mask:0xf
	v_fmac_f32_dpp v195, v11, v113 row_shr:1 row_mask:0xf bank_mask:0xf
	v_fmac_f32_dpp v188, v20, v154 row_shr:2 row_mask:0xf bank_mask:0xf
	v_fmac_f32_dpp v189, v21, v155 row_shr:2 row_mask:0xf bank_mask:0xf
	v_fmac_f32_dpp v190, v22, v156 row_shr:2 row_mask:0xf bank_mask:0xf
	v_fmac_f32_dpp v191, v23, v157 row_shr:2 row_mask:0xf bank_mask:0xf
	v_fmac_f32_dpp v192, v8, v118 row_shr:2 row_mask:0xf bank_mask:0xf
	v_fmac_f32_dpp v193, v9, v119 row_shr:2 row_mask:0xf bank_mask:0xf
	v_fmac_f32_dpp v194, v10, v120 row_shr:2 row_mask:0xf bank_mask:0xf
	v_fmac_f32_dpp v195, v11, v121 row_shr:2 row_mask:0xf bank_mask:0xf
	v_fmac_f32_dpp v188, v24, v142 row_shl:15 row_mask:0xf bank_mask:0xf
	v_fmac_f32_dpp v189, v25, v143 row_shl:15 row_mask:0xf bank_mask:0xf
	v_fmac_f32_dpp v190, v26, v144 row_shl:15 row_mask:0xf bank_mask:0xf
	v_fmac_f32_dpp v191, v27, v145 row_shl:15 row_mask:0xf bank_mask:0xf
	v_fmac_f32_dpp v192, v12, v110 row_shl:15 row_mask:0xf bank_mask:0xf
	v_fmac_f32_dpp v193, v13, v111 row_shl:15 row_mask:0xf bank_mask:0xf
	v_fmac_f32_dpp v194, v14, v112 row_shl:15 row_mask:0xf bank_mask:0xf
	v_fmac_f32_dpp v195, v15, v113 row_shl:15 row_mask:0xf bank_mask:0xf
	v_fmac_f32_dpp v188, v24, v154 row_shl:14 row_mask:0xf bank_mask:0xf
	v_fmac_f32_dpp v189, v25, v155 row_shl:14 row_mask:0xf bank_mask:0xf
	v_fmac_f32_dpp v190, v26, v156 row_shl:14 row_mask:0xf bank_mask:0xf
	v_fmac_f32_dpp v191, v27, v157 row_shl:14 row_mask:0xf bank_mask:0xf
	v_fmac_f32_dpp v192, v12, v118 row_shl:14 row_mask:0xf bank_mask:0xf
	v_fmac_f32_dpp v193, v13, v119 row_shl:14 row_mask:0xf bank_mask:0xf
	v_fmac_f32_dpp v194, v14, v120 row_shl:14 row_mask:0xf bank_mask:0xf
	v_fmac_f32_dpp v195, v15, v121 row_shl:14 row_mask:0xf bank_mask:0xf
	v_pk_mul_f32 v[196:197], v[188:189], v[216:217] op_sel_hi:[1,0]
	v_pk_mul_f32 v[198:199], v[190:191], v[216:217] op_sel_hi:[1,0]
	v_exp_f32_e32 v196, v196
	v_exp_f32_e32 v197, v197
	v_exp_f32_e32 v198, v198
	v_exp_f32_e32 v199, v199
	v_pk_add_f32 v[196:197], v[196:197], v[214:215] op_sel_hi:[1,0]
	v_pk_add_f32 v[198:199], v[198:199], v[214:215] op_sel_hi:[1,0]
	v_rcp_f32_e32 v196, v196
	v_rcp_f32_e32 v197, v197
	v_rcp_f32_e32 v198, v198
	v_rcp_f32_e32 v199, v199
	v_pk_mul_f32 v[188:189], v[188:189], v[196:197]
	v_pk_mul_f32 v[190:191], v[190:191], v[198:199]
	v_pk_mul_f32 v[188:189], v[188:189], v[192:193]
	v_pk_mul_f32 v[190:191], v[190:191], v[194:195]
	v_cvt_pk_bf16_f32 v124, v188, v189
	v_cvt_pk_bf16_f32 v125, v190, v191
	v_add_u32_e32 v213, 0x108000, v215
	global_store_dwordx4 v213, v[122:125], s[96:97] nt
	v_pk_fma_f32 v[188:189], v[4:5], v[134:135], v[130:131]
	v_pk_fma_f32 v[190:191], v[6:7], v[136:137], v[132:133]
	v_pk_fma_f32 v[192:193], v[0:1], v[204:205], v[208:209]
	v_pk_fma_f32 v[194:195], v[2:3], v[206:207], v[210:211]
	v_fmac_f32_dpp v188, v4, v142 row_shr:1 row_mask:0xf bank_mask:0xf
	v_fmac_f32_dpp v189, v5, v143 row_shr:1 row_mask:0xf bank_mask:0xf
	v_fmac_f32_dpp v190, v6, v144 row_shr:1 row_mask:0xf bank_mask:0xf
	v_fmac_f32_dpp v191, v7, v145 row_shr:1 row_mask:0xf bank_mask:0xf
	v_fmac_f32_dpp v192, v0, v110 row_shr:1 row_mask:0xf bank_mask:0xf
	v_fmac_f32_dpp v193, v1, v111 row_shr:1 row_mask:0xf bank_mask:0xf
	v_fmac_f32_dpp v194, v2, v112 row_shr:1 row_mask:0xf bank_mask:0xf
	v_fmac_f32_dpp v195, v3, v113 row_shr:1 row_mask:0xf bank_mask:0xf
	v_fmac_f32_dpp v188, v4, v154 row_shr:2 row_mask:0xf bank_mask:0xf
	v_fmac_f32_dpp v189, v5, v155 row_shr:2 row_mask:0xf bank_mask:0xf
	v_fmac_f32_dpp v190, v6, v156 row_shr:2 row_mask:0xf bank_mask:0xf
	v_fmac_f32_dpp v191, v7, v157 row_shr:2 row_mask:0xf bank_mask:0xf
	v_fmac_f32_dpp v192, v0, v118 row_shr:2 row_mask:0xf bank_mask:0xf
	v_fmac_f32_dpp v193, v1, v119 row_shr:2 row_mask:0xf bank_mask:0xf
	v_fmac_f32_dpp v194, v2, v120 row_shr:2 row_mask:0xf bank_mask:0xf
	v_fmac_f32_dpp v195, v3, v121 row_shr:2 row_mask:0xf bank_mask:0xf
	v_fmac_f32_dpp v188, v20, v142 row_shl:15 row_mask:0xf bank_mask:0xf
	v_fmac_f32_dpp v189, v21, v143 row_shl:15 row_mask:0xf bank_mask:0xf
	v_fmac_f32_dpp v190, v22, v144 row_shl:15 row_mask:0xf bank_mask:0xf
	v_fmac_f32_dpp v191, v23, v145 row_shl:15 row_mask:0xf bank_mask:0xf
	v_fmac_f32_dpp v192, v8, v110 row_shl:15 row_mask:0xf bank_mask:0xf
	v_fmac_f32_dpp v193, v9, v111 row_shl:15 row_mask:0xf bank_mask:0xf
	v_fmac_f32_dpp v194, v10, v112 row_shl:15 row_mask:0xf bank_mask:0xf
	v_fmac_f32_dpp v195, v11, v113 row_shl:15 row_mask:0xf bank_mask:0xf
	v_fmac_f32_dpp v188, v20, v154 row_shl:14 row_mask:0xf bank_mask:0xf
	v_fmac_f32_dpp v189, v21, v155 row_shl:14 row_mask:0xf bank_mask:0xf
	v_fmac_f32_dpp v190, v22, v156 row_shl:14 row_mask:0xf bank_mask:0xf
	v_fmac_f32_dpp v191, v23, v157 row_shl:14 row_mask:0xf bank_mask:0xf
	v_fmac_f32_dpp v192, v8, v118 row_shl:14 row_mask:0xf bank_mask:0xf
	v_fmac_f32_dpp v193, v9, v119 row_shl:14 row_mask:0xf bank_mask:0xf
	v_fmac_f32_dpp v194, v10, v120 row_shl:14 row_mask:0xf bank_mask:0xf
	v_fmac_f32_dpp v195, v11, v121 row_shl:14 row_mask:0xf bank_mask:0xf
	v_pk_mul_f32 v[196:197], v[188:189], v[216:217] op_sel_hi:[1,0]
	v_pk_mul_f32 v[198:199], v[190:191], v[216:217] op_sel_hi:[1,0]
	v_exp_f32_e32 v196, v196
	v_exp_f32_e32 v197, v197
	v_exp_f32_e32 v198, v198
	v_exp_f32_e32 v199, v199
	v_pk_add_f32 v[196:197], v[196:197], v[214:215] op_sel_hi:[1,0]
	v_pk_add_f32 v[198:199], v[198:199], v[214:215] op_sel_hi:[1,0]
	v_rcp_f32_e32 v196, v196
	v_rcp_f32_e32 v197, v197
	v_rcp_f32_e32 v198, v198
	v_rcp_f32_e32 v199, v199
	v_pk_mul_f32 v[188:189], v[188:189], v[196:197]
	v_pk_mul_f32 v[190:191], v[190:191], v[198:199]
	v_pk_mul_f32 v[188:189], v[188:189], v[192:193]
	v_pk_mul_f32 v[190:191], v[190:191], v[194:195]
	v_cvt_pk_bf16_f32 v116, v188, v189
	v_cvt_pk_bf16_f32 v117, v190, v191
	v_add_u32_e32 v213, 0x134000, v215
	global_store_dwordx4 v213, v[114:117], s[96:97] nt
	s_branch .LBB0_836
